# GEMM tile boundary: keep the wave-half stagger through the epilogue (wr0 extra barrier moved to phase exit, wr1 re-stagger barrier removed) in all 6 GEMM phases
# baseline (speedup 1.0000x reference)
.LBB0_216:
	s_add_u32 s28, s50, 0xfff80080
	s_addc_u32 s29, s51, -1
	s_add_i32 s89, 0, 0x10000
	s_cmp_eq_u32 s88, 28
	s_cselect_b32 s53, s43, s29
	s_cselect_b32 s52, s84, s28
	s_cselect_b32 s29, s41, s87
	s_cselect_b32 s28, s85, s86
	s_add_i32 s92, 0, 0x14000
	v_add_u32_e32 v158, s89, v147
	v_add_u32_e32 v174, s92, v147
	ds_read_b128 v[142:145], v158
	ds_read_b128 v[150:153], v158 offset:1024
	ds_read_b128 v[154:157], v158 offset:2048
	ds_read_b128 v[158:161], v158 offset:3072
	ds_read_b128 v[162:165], v174
	ds_read_b128 v[166:169], v174 offset:1024
	ds_read_b128 v[170:173], v174 offset:2048
	ds_read_b128 v[174:177], v174 offset:3072
	v_lshl_add_u64 v[206:207], s[50:51], 0, v[138:139]
	s_add_i32 m0, s36, 0xc000
	ds_read_b128 v[178:181], v149
	ds_read_b128 v[182:185], v149 offset:1024
	ds_read_b128 v[186:189], v149 offset:2048
	ds_read_b128 v[190:193], v149 offset:3072
	ds_read_b128 v[194:197], v149 offset:4096
	ds_read_b128 v[198:201], v149 offset:5120
	ds_read_b128 v[202:205], v149 offset:6144
	ds_read_b128 v[224:227], v149 offset:7168
	global_load_lds_dwordx4 v[206:207], off
	v_lshl_add_u64 v[206:207], s[50:51], 0, v[140:141]
	s_add_i32 m0, s36, 0xe000
	s_nop 0
	global_load_lds_dwordx4 v[206:207], off
	s_waitcnt vmcnt(8)
	s_waitcnt lgkmcnt(0)
	s_barrier
	s_setprio 1
	s_waitcnt lgkmcnt(0)
	v_mfma_f32_16x16x32_bf16 v[126:129], v[142:145], v[178:181], v[126:129]
	v_mfma_f32_16x16x32_bf16 v[122:125], v[154:157], v[178:181], v[122:125]
	v_mfma_f32_16x16x32_bf16 v[118:121], v[142:145], v[186:189], v[118:121]
	v_mfma_f32_16x16x32_bf16 v[110:113], v[154:157], v[186:189], v[110:113]
	v_mfma_f32_16x16x32_bf16 v[102:105], v[142:145], v[194:197], v[102:105]
	v_mfma_f32_16x16x32_bf16 v[94:97], v[154:157], v[194:197], v[94:97]
	v_mfma_f32_16x16x32_bf16 v[86:89], v[142:145], v[202:205], v[86:89]
	v_mfma_f32_16x16x32_bf16 v[78:81], v[154:157], v[202:205], v[78:81]
	v_mfma_f32_16x16x32_bf16 v[126:129], v[150:153], v[182:185], v[126:129]
	v_mfma_f32_16x16x32_bf16 v[122:125], v[158:161], v[182:185], v[122:125]
	v_mfma_f32_16x16x32_bf16 v[118:121], v[150:153], v[190:193], v[118:121]
	v_mfma_f32_16x16x32_bf16 v[110:113], v[158:161], v[190:193], v[110:113]
	v_mfma_f32_16x16x32_bf16 v[102:105], v[150:153], v[198:201], v[102:105]
	v_mfma_f32_16x16x32_bf16 v[94:97], v[158:161], v[198:201], v[94:97]
	v_mfma_f32_16x16x32_bf16 v[86:89], v[150:153], v[224:227], v[86:89]
	v_mfma_f32_16x16x32_bf16 v[78:81], v[158:161], v[224:227], v[78:81]
	s_setprio 0
	s_setprio 1
	v_mfma_f32_16x16x32_bf16 v[114:117], v[162:165], v[178:181], v[114:117]
	v_mfma_f32_16x16x32_bf16 v[106:109], v[170:173], v[178:181], v[106:109]
	v_mfma_f32_16x16x32_bf16 v[98:101], v[162:165], v[186:189], v[98:101]
	v_mfma_f32_16x16x32_bf16 v[90:93], v[170:173], v[186:189], v[90:93]
	v_mfma_f32_16x16x32_bf16 v[82:85], v[162:165], v[194:197], v[82:85]
	v_mfma_f32_16x16x32_bf16 v[74:77], v[170:173], v[194:197], v[74:77]
	v_mfma_f32_16x16x32_bf16 v[70:73], v[162:165], v[202:205], v[70:73]
	v_mfma_f32_16x16x32_bf16 v[66:69], v[170:173], v[202:205], v[66:69]
	v_mfma_f32_16x16x32_bf16 v[114:117], v[166:169], v[182:185], v[114:117]
	v_mfma_f32_16x16x32_bf16 v[106:109], v[174:177], v[182:185], v[106:109]
	v_mfma_f32_16x16x32_bf16 v[98:101], v[166:169], v[190:193], v[98:101]
	v_mfma_f32_16x16x32_bf16 v[90:93], v[174:177], v[190:193], v[90:93]
	v_mfma_f32_16x16x32_bf16 v[82:85], v[166:169], v[198:201], v[82:85]
	v_mfma_f32_16x16x32_bf16 v[74:77], v[174:177], v[198:201], v[74:77]
	v_mfma_f32_16x16x32_bf16 v[70:73], v[166:169], v[224:227], v[70:73]
	v_mfma_f32_16x16x32_bf16 v[66:69], v[174:177], v[224:227], v[66:69]
	s_setprio 0
	s_barrier
	s_add_i32 s89, s89, s26
	v_lshl_add_u64 v[206:207], s[28:29], 0, v[134:135]
	s_mov_b32 m0, s89
	ds_read_b128 v[178:181], v149 offset:16384
	ds_read_b128 v[182:185], v149 offset:17408
	ds_read_b128 v[186:189], v149 offset:18432
	ds_read_b128 v[190:193], v149 offset:19456
	ds_read_b128 v[194:197], v149 offset:20480
	ds_read_b128 v[198:201], v149 offset:21504
	ds_read_b128 v[202:205], v149 offset:22528
	ds_read_b128 v[224:227], v149 offset:23552
	global_load_lds_dwordx4 v[206:207], off
	s_add_i32 m0, s89, 0x2000
	s_add_u32 s90, s28, 0x80000
	v_lshl_add_u64 v[228:229], s[28:29], 0, v[130:131]
	s_addc_u32 s91, s29, 0
	s_add_i32 s89, s92, s26
	global_load_lds_dwordx4 v[228:229], off
	v_lshl_add_u64 v[230:231], s[90:91], 0, v[134:135]
	s_mov_b32 m0, s89
	v_lshl_add_u64 v[232:233], s[52:53], 0, v[132:133]
	global_load_lds_dwordx4 v[230:231], off
	v_lshl_add_u64 v[230:231], s[90:91], 0, v[130:131]
	s_add_i32 m0, s89, 0x2000
	s_nop 0
	global_load_lds_dwordx4 v[230:231], off
	v_lshl_add_u64 v[230:231], s[52:53], 0, v[136:137]
	s_mov_b32 m0, s36
	s_nop 0
	global_load_lds_dwordx4 v[230:231], off
	s_mov_b32 m0, s37
	s_nop 0
	global_load_lds_dwordx4 v[232:233], off
	s_waitcnt vmcnt(8)
	s_waitcnt lgkmcnt(0)
	s_barrier
	s_setprio 1
	s_waitcnt lgkmcnt(0)
	v_mfma_f32_16x16x32_bf16 v[62:65], v[142:145], v[178:181], v[62:65]
	v_mfma_f32_16x16x32_bf16 v[58:61], v[154:157], v[178:181], v[58:61]
	v_mfma_f32_16x16x32_bf16 v[54:57], v[142:145], v[186:189], v[54:57]
	v_mfma_f32_16x16x32_bf16 v[46:49], v[154:157], v[186:189], v[46:49]
	v_mfma_f32_16x16x32_bf16 v[38:41], v[142:145], v[194:197], v[38:41]
	v_mfma_f32_16x16x32_bf16 v[30:33], v[154:157], v[194:197], v[30:33]
	v_mfma_f32_16x16x32_bf16 v[22:25], v[142:145], v[202:205], v[22:25]
	v_mfma_f32_16x16x32_bf16 v[12:15], v[154:157], v[202:205], v[12:15]
	v_mfma_f32_16x16x32_bf16 v[62:65], v[150:153], v[182:185], v[62:65]
	v_mfma_f32_16x16x32_bf16 v[58:61], v[158:161], v[182:185], v[58:61]
	v_mfma_f32_16x16x32_bf16 v[54:57], v[150:153], v[190:193], v[54:57]
	v_mfma_f32_16x16x32_bf16 v[46:49], v[158:161], v[190:193], v[46:49]
	v_mfma_f32_16x16x32_bf16 v[38:41], v[150:153], v[198:201], v[38:41]
	v_mfma_f32_16x16x32_bf16 v[30:33], v[158:161], v[198:201], v[30:33]
	v_mfma_f32_16x16x32_bf16 v[22:25], v[150:153], v[224:227], v[22:25]
	v_mfma_f32_16x16x32_bf16 v[12:15], v[158:161], v[224:227], v[12:15]
	s_setprio 0
	s_setprio 1
	v_mfma_f32_16x16x32_bf16 v[50:53], v[162:165], v[178:181], v[50:53]
	v_mfma_f32_16x16x32_bf16 v[42:45], v[170:173], v[178:181], v[42:45]
	v_mfma_f32_16x16x32_bf16 v[34:37], v[162:165], v[186:189], v[34:37]
	v_mfma_f32_16x16x32_bf16 v[26:29], v[170:173], v[186:189], v[26:29]
	v_mfma_f32_16x16x32_bf16 v[18:21], v[162:165], v[194:197], v[18:21]
	v_mfma_f32_16x16x32_bf16 v[8:11], v[170:173], v[194:197], v[8:11]
	v_mfma_f32_16x16x32_bf16 v[4:7], v[162:165], v[202:205], v[4:7]
	v_mfma_f32_16x16x32_bf16 v[0:3], v[170:173], v[202:205], v[0:3]
	v_mfma_f32_16x16x32_bf16 v[50:53], v[166:169], v[182:185], v[50:53]
	v_mfma_f32_16x16x32_bf16 v[42:45], v[174:177], v[182:185], v[42:45]
	v_mfma_f32_16x16x32_bf16 v[34:37], v[166:169], v[190:193], v[34:37]
	v_mfma_f32_16x16x32_bf16 v[26:29], v[174:177], v[190:193], v[26:29]
	v_mfma_f32_16x16x32_bf16 v[18:21], v[166:169], v[198:201], v[18:21]
	v_mfma_f32_16x16x32_bf16 v[8:11], v[174:177], v[198:201], v[8:11]
	v_mfma_f32_16x16x32_bf16 v[4:7], v[166:169], v[224:227], v[4:7]
	v_mfma_f32_16x16x32_bf16 v[0:3], v[174:177], v[224:227], v[0:3]
	s_setprio 0
	s_barrier
	s_add_i32 s89, 0, 0x18000
	s_add_i32 s90, 0, 0x1c000
	v_add_u32_e32 v158, s89, v147
	v_add_u32_e32 v174, s90, v147
	ds_read_b128 v[142:145], v158
	ds_read_b128 v[150:153], v158 offset:1024
	ds_read_b128 v[154:157], v158 offset:2048
	ds_read_b128 v[158:161], v158 offset:3072
	ds_read_b128 v[162:165], v174
	ds_read_b128 v[166:169], v174 offset:1024
	ds_read_b128 v[170:173], v174 offset:2048
	ds_read_b128 v[174:177], v174 offset:3072
	s_add_u32 s52, s52, 0x80000
	s_addc_u32 s53, s53, 0
	s_mov_b32 m0, s49
	v_lshl_add_u64 v[234:235], s[52:53], 0, v[136:137]
	ds_read_b128 v[178:181], v149 offset:32768
	ds_read_b128 v[182:185], v149 offset:33792
	ds_read_b128 v[186:189], v149 offset:34816
	ds_read_b128 v[190:193], v149 offset:35840
	ds_read_b128 v[194:197], v149 offset:36864
	ds_read_b128 v[198:201], v149 offset:37888
	ds_read_b128 v[202:205], v149 offset:38912
	ds_read_b128 v[224:227], v149 offset:39936
	global_load_lds_dwordx4 v[234:235], off
	v_lshl_add_u64 v[234:235], s[52:53], 0, v[132:133]
	s_mov_b32 m0, s56
	s_nop 0
	global_load_lds_dwordx4 v[234:235], off
	s_waitcnt vmcnt(8)
	s_waitcnt lgkmcnt(0)
	s_barrier
	s_setprio 1
	s_waitcnt lgkmcnt(0)
	v_mfma_f32_16x16x32_bf16 v[126:129], v[142:145], v[178:181], v[126:129]
	v_mfma_f32_16x16x32_bf16 v[122:125], v[154:157], v[178:181], v[122:125]
	v_mfma_f32_16x16x32_bf16 v[118:121], v[142:145], v[186:189], v[118:121]
	v_mfma_f32_16x16x32_bf16 v[110:113], v[154:157], v[186:189], v[110:113]
	v_mfma_f32_16x16x32_bf16 v[102:105], v[142:145], v[194:197], v[102:105]
	v_mfma_f32_16x16x32_bf16 v[94:97], v[154:157], v[194:197], v[94:97]
	v_mfma_f32_16x16x32_bf16 v[86:89], v[142:145], v[202:205], v[86:89]
	v_mfma_f32_16x16x32_bf16 v[78:81], v[154:157], v[202:205], v[78:81]
	v_mfma_f32_16x16x32_bf16 v[126:129], v[150:153], v[182:185], v[126:129]
	v_mfma_f32_16x16x32_bf16 v[122:125], v[158:161], v[182:185], v[122:125]
	v_mfma_f32_16x16x32_bf16 v[118:121], v[150:153], v[190:193], v[118:121]
	v_mfma_f32_16x16x32_bf16 v[110:113], v[158:161], v[190:193], v[110:113]
	v_mfma_f32_16x16x32_bf16 v[102:105], v[150:153], v[198:201], v[102:105]
	v_mfma_f32_16x16x32_bf16 v[94:97], v[158:161], v[198:201], v[94:97]
	v_mfma_f32_16x16x32_bf16 v[86:89], v[150:153], v[224:227], v[86:89]
	v_mfma_f32_16x16x32_bf16 v[78:81], v[158:161], v[224:227], v[78:81]
	s_setprio 0
	s_setprio 1
	v_mfma_f32_16x16x32_bf16 v[114:117], v[162:165], v[178:181], v[114:117]
	v_mfma_f32_16x16x32_bf16 v[106:109], v[170:173], v[178:181], v[106:109]
	v_mfma_f32_16x16x32_bf16 v[98:101], v[162:165], v[186:189], v[98:101]
	v_mfma_f32_16x16x32_bf16 v[90:93], v[170:173], v[186:189], v[90:93]
	v_mfma_f32_16x16x32_bf16 v[82:85], v[162:165], v[194:197], v[82:85]
	v_mfma_f32_16x16x32_bf16 v[74:77], v[170:173], v[194:197], v[74:77]
	v_mfma_f32_16x16x32_bf16 v[70:73], v[162:165], v[202:205], v[70:73]
	v_mfma_f32_16x16x32_bf16 v[66:69], v[170:173], v[202:205], v[66:69]
	v_mfma_f32_16x16x32_bf16 v[114:117], v[166:169], v[182:185], v[114:117]
	v_mfma_f32_16x16x32_bf16 v[106:109], v[174:177], v[182:185], v[106:109]
	v_mfma_f32_16x16x32_bf16 v[98:101], v[166:169], v[190:193], v[98:101]
	v_mfma_f32_16x16x32_bf16 v[90:93], v[174:177], v[190:193], v[90:93]
	v_mfma_f32_16x16x32_bf16 v[82:85], v[166:169], v[198:201], v[82:85]
	v_mfma_f32_16x16x32_bf16 v[74:77], v[174:177], v[198:201], v[74:77]
	v_mfma_f32_16x16x32_bf16 v[70:73], v[166:169], v[224:227], v[70:73]
	v_mfma_f32_16x16x32_bf16 v[66:69], v[174:177], v[224:227], v[66:69]
	s_setprio 0
	s_barrier
	s_add_i32 s52, s89, s26
	v_lshl_add_u64 v[206:207], v[206:207], 0, s[34:35]
	s_mov_b32 m0, s52
	ds_read_b128 v[178:181], v149 offset:49152
	ds_read_b128 v[182:185], v149 offset:50176
	ds_read_b128 v[186:189], v149 offset:51200
	ds_read_b128 v[190:193], v149 offset:52224
	ds_read_b128 v[194:197], v149 offset:53248
	ds_read_b128 v[198:201], v149 offset:54272
	ds_read_b128 v[202:205], v149 offset:55296
	ds_read_b128 v[224:227], v149 offset:56320
	global_load_lds_dwordx4 v[206:207], off
	s_add_i32 m0, s52, 0x2000
	s_add_u32 s28, s28, 0x80080
	v_lshl_add_u64 v[206:207], v[228:229], 0, s[34:35]
	s_addc_u32 s29, s29, 0
	s_add_i32 s52, s90, s26
	global_load_lds_dwordx4 v[206:207], off
	v_lshl_add_u64 v[206:207], s[28:29], 0, v[134:135]
	s_mov_b32 m0, s52
	s_nop 0
	global_load_lds_dwordx4 v[206:207], off
	v_lshl_add_u64 v[206:207], s[28:29], 0, v[130:131]
	s_add_i32 m0, s52, 0x2000
	s_nop 0
	global_load_lds_dwordx4 v[206:207], off
	v_lshl_add_u64 v[206:207], v[230:231], 0, s[34:35]
	s_mov_b32 m0, s57
	s_nop 0
	global_load_lds_dwordx4 v[206:207], off
	v_lshl_add_u64 v[206:207], v[232:233], 0, s[34:35]
	s_mov_b32 m0, s58
	s_nop 0
	global_load_lds_dwordx4 v[206:207], off
	s_waitcnt vmcnt(8)
	s_waitcnt lgkmcnt(0)
	s_barrier
	s_setprio 1
	s_waitcnt lgkmcnt(0)
	v_mfma_f32_16x16x32_bf16 v[62:65], v[142:145], v[178:181], v[62:65]
	v_mfma_f32_16x16x32_bf16 v[58:61], v[154:157], v[178:181], v[58:61]
	v_mfma_f32_16x16x32_bf16 v[54:57], v[142:145], v[186:189], v[54:57]
	v_mfma_f32_16x16x32_bf16 v[46:49], v[154:157], v[186:189], v[46:49]
	v_mfma_f32_16x16x32_bf16 v[38:41], v[142:145], v[194:197], v[38:41]
	v_mfma_f32_16x16x32_bf16 v[30:33], v[154:157], v[194:197], v[30:33]
	v_mfma_f32_16x16x32_bf16 v[22:25], v[142:145], v[202:205], v[22:25]
	v_mfma_f32_16x16x32_bf16 v[12:15], v[154:157], v[202:205], v[12:15]
	v_mfma_f32_16x16x32_bf16 v[62:65], v[150:153], v[182:185], v[62:65]
	v_mfma_f32_16x16x32_bf16 v[58:61], v[158:161], v[182:185], v[58:61]
	v_mfma_f32_16x16x32_bf16 v[54:57], v[150:153], v[190:193], v[54:57]
	v_mfma_f32_16x16x32_bf16 v[46:49], v[158:161], v[190:193], v[46:49]
	v_mfma_f32_16x16x32_bf16 v[38:41], v[150:153], v[198:201], v[38:41]
	v_mfma_f32_16x16x32_bf16 v[30:33], v[158:161], v[198:201], v[30:33]
	v_mfma_f32_16x16x32_bf16 v[22:25], v[150:153], v[224:227], v[22:25]
	v_mfma_f32_16x16x32_bf16 v[12:15], v[158:161], v[224:227], v[12:15]
	s_setprio 0
	s_setprio 1
	v_mfma_f32_16x16x32_bf16 v[50:53], v[162:165], v[178:181], v[50:53]
	v_mfma_f32_16x16x32_bf16 v[42:45], v[170:173], v[178:181], v[42:45]
	v_mfma_f32_16x16x32_bf16 v[34:37], v[162:165], v[186:189], v[34:37]
	v_mfma_f32_16x16x32_bf16 v[26:29], v[170:173], v[186:189], v[26:29]
	v_mfma_f32_16x16x32_bf16 v[18:21], v[162:165], v[194:197], v[18:21]
	v_mfma_f32_16x16x32_bf16 v[8:11], v[170:173], v[194:197], v[8:11]
	v_mfma_f32_16x16x32_bf16 v[4:7], v[162:165], v[202:205], v[4:7]
	v_mfma_f32_16x16x32_bf16 v[0:3], v[170:173], v[202:205], v[0:3]
	v_mfma_f32_16x16x32_bf16 v[50:53], v[166:169], v[182:185], v[50:53]
	v_mfma_f32_16x16x32_bf16 v[42:45], v[174:177], v[182:185], v[42:45]
	v_mfma_f32_16x16x32_bf16 v[34:37], v[166:169], v[190:193], v[34:37]
	v_mfma_f32_16x16x32_bf16 v[26:29], v[174:177], v[190:193], v[26:29]
	v_mfma_f32_16x16x32_bf16 v[18:21], v[166:169], v[198:201], v[18:21]
	v_mfma_f32_16x16x32_bf16 v[8:11], v[174:177], v[198:201], v[8:11]
	v_mfma_f32_16x16x32_bf16 v[4:7], v[166:169], v[224:227], v[4:7]
	v_mfma_f32_16x16x32_bf16 v[0:3], v[174:177], v[224:227], v[0:3]
	s_setprio 0
	s_barrier
	s_add_i32 s88, s88, 2
	s_add_u32 s50, s50, 0x100
	s_addc_u32 s51, s51, 0
	s_add_u32 s86, s86, 0x100
	s_addc_u32 s87, s87, 0
	s_cmp_gt_u32 s88, 29
	s_cbranch_scc0 .LBB0_216
	s_and_b64 vcc, exec, s[18:19]
	s_cbranch_vccz .LBB0_221
	s_cmp_gt_i32 s83, 13
	s_mov_b64 s[28:29], -1
	s_cbranch_scc1 .LBB0_222

.LBB0_224:
	s_andn2_b64 vcc, exec, s[0:1]
	s_cbranch_vccnz .LBB0_211
	s_branch .LBB0_211
.LBB0_226:
	s_and_b64 vcc, exec, s[18:19]
	s_cbranch_vccz .Lsg_B_nb
	s_barrier

.LBB0_652:
	v_lshl_add_u32 v146, s44, 8, v142
	v_lshl_or_b32 v140, s86, 8, v144
	v_ashrrev_i32_e32 v147, 31, v146
	v_ashrrev_i32_e32 v141, 31, v140
	v_lshlrev_b64 v[148:149], 14, v[146:147]
	v_lshl_add_u64 v[148:149], s[70:71], 0, v[148:149]
	v_lshlrev_b64 v[150:151], 1, v[140:141]
	v_lshl_add_u64 v[140:141], v[148:149], 0, v[150:151]
	v_cvt_pk_bf16_f32 v126, v126, v127
	v_cvt_pk_bf16_f32 v127, v128, v129
	v_cvt_pk_bf16_f32 v128, v122, v123
	v_cvt_pk_bf16_f32 v129, v124, v125
	global_store_dwordx4 v[140:141], v[126:129], off
	v_cvt_pk_bf16_f32 v114, v114, v115
	v_cvt_pk_bf16_f32 v115, v116, v117
	v_cvt_pk_bf16_f32 v116, v106, v107
	v_or_b32_e32 v106, 16, v146
	v_ashrrev_i32_e32 v107, 31, v106
	v_lshlrev_b64 v[106:107], 14, v[106:107]
	v_lshl_add_u64 v[106:107], s[70:71], 0, v[106:107]
	v_cvt_pk_bf16_f32 v117, v108, v109
	global_store_dwordx4 v[140:141], v[114:117], off offset:256
	s_mov_b32 s19, 0x200000
	s_mov_b64 s[28:29], 0x200000
	v_lshl_add_u64 v[114:115], v[106:107], 0, v[150:151]
	v_cvt_pk_bf16_f32 v106, v118, v119
	v_cvt_pk_bf16_f32 v107, v120, v121
	v_cvt_pk_bf16_f32 v108, v110, v111
	v_cvt_pk_bf16_f32 v109, v112, v113
	global_store_dwordx4 v[114:115], v[106:109], off
	v_cvt_pk_bf16_f32 v98, v98, v99
	v_cvt_pk_bf16_f32 v99, v100, v101
	v_cvt_pk_bf16_f32 v100, v90, v91
	v_or_b32_e32 v90, 32, v146
	v_ashrrev_i32_e32 v91, 31, v90
	v_lshlrev_b64 v[90:91], 14, v[90:91]
	v_lshl_add_u64 v[90:91], s[70:71], 0, v[90:91]
	v_cvt_pk_bf16_f32 v101, v92, v93
	global_store_dwordx4 v[114:115], v[98:101], off offset:256
	s_mov_b64 s[90:91], s[62:63]
	s_nop 0
	v_lshl_add_u64 v[98:99], v[90:91], 0, v[150:151]
	v_cvt_pk_bf16_f32 v90, v102, v103
	v_cvt_pk_bf16_f32 v91, v104, v105
	v_cvt_pk_bf16_f32 v92, v94, v95
	v_cvt_pk_bf16_f32 v93, v96, v97
	global_store_dwordx4 v[98:99], v[90:93], off
	v_cvt_pk_bf16_f32 v82, v82, v83
	v_cvt_pk_bf16_f32 v83, v84, v85
	v_cvt_pk_bf16_f32 v84, v74, v75
	v_or_b32_e32 v74, 48, v146
	v_ashrrev_i32_e32 v75, 31, v74
	v_lshlrev_b64 v[74:75], 14, v[74:75]
	v_lshl_add_u64 v[74:75], s[70:71], 0, v[74:75]
	v_cvt_pk_bf16_f32 v85, v76, v77
	global_store_dwordx4 v[98:99], v[82:85], off offset:256
	s_nop 1
	v_lshl_add_u64 v[82:83], v[74:75], 0, v[150:151]
	v_cvt_pk_bf16_f32 v74, v86, v87
	v_cvt_pk_bf16_f32 v75, v88, v89
	v_cvt_pk_bf16_f32 v76, v78, v79
	v_cvt_pk_bf16_f32 v77, v80, v81
	global_store_dwordx4 v[82:83], v[74:77], off
	v_cvt_pk_bf16_f32 v70, v70, v71
	v_cvt_pk_bf16_f32 v71, v72, v73
	v_cvt_pk_bf16_f32 v72, v66, v67
	v_cvt_pk_bf16_f32 v73, v68, v69
	global_store_dwordx4 v[82:83], v[70:73], off offset:256
	v_cvt_pk_bf16_f32 v62, v62, v63
	v_cvt_pk_bf16_f32 v63, v64, v65
	v_cvt_pk_bf16_f32 v64, v58, v59
	v_add_co_u32_e32 v58, vcc, s19, v140
	v_lshl_add_u64 v[66:67], v[140:141], 0, s[28:29]
	s_nop 0
	v_addc_co_u32_e32 v59, vcc, 0, v141, vcc
	s_mov_b32 s19, 0x240000
	v_cvt_pk_bf16_f32 v65, v60, v61
	global_store_dwordx4 v[58:59], v[62:65], off
	v_cvt_pk_bf16_f32 v50, v50, v51
	v_cvt_pk_bf16_f32 v51, v52, v53
	v_cvt_pk_bf16_f32 v52, v42, v43
	v_cvt_pk_bf16_f32 v53, v44, v45
	global_store_dwordx4 v[66:67], v[50:53], off offset:256
	s_mov_b64 s[28:29], 0x240000
	v_cvt_pk_bf16_f32 v42, v54, v55
	v_cvt_pk_bf16_f32 v43, v56, v57
	v_cvt_pk_bf16_f32 v44, v46, v47
	v_add_co_u32_e32 v46, vcc, s19, v140
	v_lshl_add_u64 v[50:51], v[140:141], 0, s[28:29]
	s_nop 0
	v_addc_co_u32_e32 v47, vcc, 0, v141, vcc
	s_mov_b32 s19, 0x280000
	v_cvt_pk_bf16_f32 v45, v48, v49
	global_store_dwordx4 v[46:47], v[42:45], off
	v_cvt_pk_bf16_f32 v34, v34, v35
	v_cvt_pk_bf16_f32 v35, v36, v37
	v_cvt_pk_bf16_f32 v36, v26, v27
	v_cvt_pk_bf16_f32 v37, v28, v29
	global_store_dwordx4 v[50:51], v[34:37], off offset:256
	s_mov_b64 s[28:29], 0x280000
	v_cvt_pk_bf16_f32 v26, v38, v39
	v_cvt_pk_bf16_f32 v27, v40, v41
	v_cvt_pk_bf16_f32 v28, v30, v31
	v_add_co_u32_e32 v30, vcc, s19, v140
	v_lshl_add_u64 v[34:35], v[140:141], 0, s[28:29]
	s_nop 0
	v_addc_co_u32_e32 v31, vcc, 0, v141, vcc
	s_mov_b32 s19, 0x2c0000
	v_cvt_pk_bf16_f32 v29, v32, v33
	global_store_dwordx4 v[30:31], v[26:29], off
	v_cvt_pk_bf16_f32 v18, v18, v19
	v_cvt_pk_bf16_f32 v19, v20, v21
	v_cvt_pk_bf16_f32 v20, v8, v9
	v_cvt_pk_bf16_f32 v21, v10, v11
	global_store_dwordx4 v[34:35], v[18:21], off offset:256
	v_cvt_pk_bf16_f32 v8, v22, v23
	v_cvt_pk_bf16_f32 v9, v24, v25
	v_cvt_pk_bf16_f32 v10, v12, v13
	v_add_co_u32_e32 v12, vcc, s19, v140
	s_mov_b64 s[28:29], 0x2c0000
	s_nop 0
	v_addc_co_u32_e32 v13, vcc, 0, v141, vcc
	v_lshl_add_u64 v[18:19], v[140:141], 0, s[28:29]
	s_and_b64 vcc, exec, s[38:39]
	s_mov_b64 s[28:29], -1
	v_cvt_pk_bf16_f32 v11, v14, v15
	global_store_dwordx4 v[12:13], v[8:11], off
	v_cvt_pk_bf16_f32 v4, v4, v5
	v_cvt_pk_bf16_f32 v5, v6, v7
	v_cvt_pk_bf16_f32 v6, v0, v1
	v_cvt_pk_bf16_f32 v7, v2, v3
	global_store_dwordx4 v[18:19], v[4:7], off offset:256
	s_cbranch_vccnz .LBB0_643
	s_andn2_b64 vcc, exec, s[0:1]
	s_cbranch_vccnz .LBB0_642
	s_branch .LBB0_642
.LBB0_655:
	s_and_b64 vcc, exec, s[14:15]
	s_cbranch_vccz .Lsg_E_nb
	s_barrier

.LBB0_720:
	v_lshl_add_u32 v162, s42, 8, v223
	v_lshl_or_b32 v136, s83, 6, v225
	v_ashrrev_i32_e32 v163, 31, v162
	v_lshlrev_b64 v[138:139], 14, v[162:163]
	v_ashrrev_i32_e32 v137, 31, v136
	v_lshl_add_u64 v[138:139], s[70:71], 0, v[138:139]
	v_lshlrev_b64 v[148:149], 1, v[136:137]
	v_lshl_add_u64 v[136:137], v[138:139], 0, v[148:149]
	v_add_co_u32_e32 v138, vcc, 0x1000, v136
	s_mov_b32 s19, 0x200000
	s_nop 0
	v_addc_co_u32_e32 v139, vcc, 0, v137, vcc
	v_add_co_u32_e32 v140, vcc, 0x2000, v136
	s_nop 1
	v_addc_co_u32_e32 v141, vcc, 0, v137, vcc
	v_add_co_u32_e32 v142, vcc, 0x3000, v136
	s_nop 1
	v_addc_co_u32_e32 v143, vcc, 0, v137, vcc
	global_load_dwordx2 v[200:201], v[136:137], off
	global_load_dwordx2 v[202:203], v[138:139], off
	global_load_dwordx2 v[196:197], v[140:141], off
	global_load_dwordx2 v[198:199], v[142:143], off
	v_add_co_u32_e32 v138, vcc, s20, v136
	s_nop 1
	v_addc_co_u32_e32 v139, vcc, 0, v137, vcc
	v_add_co_u32_e32 v140, vcc, 0x41000, v136
	s_nop 1
	v_addc_co_u32_e32 v141, vcc, 0, v137, vcc
	v_add_co_u32_e32 v142, vcc, 0x42000, v136
	s_nop 1
	v_addc_co_u32_e32 v143, vcc, 0, v137, vcc
	v_add_co_u32_e32 v144, vcc, 0x43000, v136
	s_nop 1
	v_addc_co_u32_e32 v145, vcc, 0, v137, vcc
	global_load_dwordx2 v[192:193], v[138:139], off
	global_load_dwordx2 v[194:195], v[140:141], off
	global_load_dwordx2 v[188:189], v[142:143], off
	global_load_dwordx2 v[190:191], v[144:145], off
	v_add_co_u32_e32 v138, vcc, s64, v136
	s_nop 1
	v_addc_co_u32_e32 v139, vcc, 0, v137, vcc
	v_add_co_u32_e32 v140, vcc, 0x81000, v136
	s_nop 1
	v_addc_co_u32_e32 v141, vcc, 0, v137, vcc
	v_add_co_u32_e32 v142, vcc, 0x82000, v136
	s_nop 1
	v_addc_co_u32_e32 v143, vcc, 0, v137, vcc
	v_add_co_u32_e32 v144, vcc, 0x83000, v136
	s_nop 1
	v_addc_co_u32_e32 v145, vcc, 0, v137, vcc
	global_load_dwordx2 v[184:185], v[138:139], off
	global_load_dwordx2 v[186:187], v[140:141], off
	global_load_dwordx2 v[180:181], v[142:143], off
	global_load_dwordx2 v[182:183], v[144:145], off
	v_add_co_u32_e32 v138, vcc, s66, v136
	s_nop 1
	v_addc_co_u32_e32 v139, vcc, 0, v137, vcc
	v_add_co_u32_e32 v140, vcc, 0xc1000, v136
	s_nop 1
	v_addc_co_u32_e32 v141, vcc, 0, v137, vcc
	v_add_co_u32_e32 v142, vcc, 0xc2000, v136
	s_nop 1
	v_addc_co_u32_e32 v143, vcc, 0, v137, vcc
	v_add_co_u32_e32 v144, vcc, 0xc3000, v136
	s_nop 1
	v_addc_co_u32_e32 v145, vcc, 0, v137, vcc
	global_load_dwordx2 v[176:177], v[138:139], off
	global_load_dwordx2 v[178:179], v[140:141], off
	global_load_dwordx2 v[172:173], v[142:143], off
	global_load_dwordx2 v[174:175], v[144:145], off
	v_add_co_u32_e32 v138, vcc, s19, v136
	s_mov_b32 s19, 0x240000
	s_nop 0
	v_addc_co_u32_e32 v139, vcc, 0, v137, vcc
	v_add_co_u32_e32 v140, vcc, 0x201000, v136
	s_nop 1
	v_addc_co_u32_e32 v141, vcc, 0, v137, vcc
	v_add_co_u32_e32 v142, vcc, 0x202000, v136
	s_nop 1
	v_addc_co_u32_e32 v143, vcc, 0, v137, vcc
	v_add_co_u32_e32 v144, vcc, 0x203000, v136
	s_nop 1
	v_addc_co_u32_e32 v145, vcc, 0, v137, vcc
	global_load_dwordx2 v[168:169], v[138:139], off
	global_load_dwordx2 v[170:171], v[140:141], off
	global_load_dwordx2 v[164:165], v[142:143], off
	global_load_dwordx2 v[166:167], v[144:145], off
	v_add_co_u32_e32 v138, vcc, s19, v136
	s_mov_b32 s19, 0x280000
	s_nop 0
	v_addc_co_u32_e32 v139, vcc, 0, v137, vcc
	v_add_co_u32_e32 v140, vcc, 0x241000, v136
	s_nop 1
	v_addc_co_u32_e32 v141, vcc, 0, v137, vcc
	v_add_co_u32_e32 v142, vcc, 0x242000, v136
	s_nop 1
	v_addc_co_u32_e32 v143, vcc, 0, v137, vcc
	v_add_co_u32_e32 v144, vcc, 0x243000, v136
	s_nop 1
	v_addc_co_u32_e32 v145, vcc, 0, v137, vcc
	global_load_dwordx2 v[158:159], v[138:139], off
	global_load_dwordx2 v[160:161], v[140:141], off
	global_load_dwordx2 v[154:155], v[142:143], off
	global_load_dwordx2 v[156:157], v[144:145], off
	v_add_co_u32_e32 v138, vcc, s19, v136
	s_mov_b32 s19, 0x2c0000
	s_nop 0
	v_addc_co_u32_e32 v139, vcc, 0, v137, vcc
	v_add_co_u32_e32 v140, vcc, 0x281000, v136
	s_nop 1
	v_addc_co_u32_e32 v141, vcc, 0, v137, vcc
	v_add_co_u32_e32 v142, vcc, 0x282000, v136
	s_nop 1
	v_addc_co_u32_e32 v143, vcc, 0, v137, vcc
	v_add_co_u32_e32 v146, vcc, 0x283000, v136
	s_nop 1
	v_addc_co_u32_e32 v147, vcc, 0, v137, vcc
	global_load_dwordx2 v[150:151], v[138:139], off
	global_load_dwordx2 v[152:153], v[140:141], off
	global_load_dwordx2 v[144:145], v[142:143], off
	s_nop 0
	global_load_dwordx2 v[146:147], v[146:147], off
	v_add_co_u32_e32 v138, vcc, s19, v136
	s_nop 1
	v_addc_co_u32_e32 v139, vcc, 0, v137, vcc
	v_add_co_u32_e32 v142, vcc, 0x2c1000, v136
	s_nop 1
	v_addc_co_u32_e32 v143, vcc, 0, v137, vcc
	v_add_co_u32_e32 v204, vcc, 0x2c2000, v136
	s_nop 1
	v_addc_co_u32_e32 v205, vcc, 0, v137, vcc
	v_add_co_u32_e32 v206, vcc, 0x2c3000, v136
	s_nop 1
	v_addc_co_u32_e32 v207, vcc, 0, v137, vcc
	global_load_dwordx2 v[140:141], v[138:139], off
	s_nop 0
	global_load_dwordx2 v[142:143], v[142:143], off
	s_nop 0
	global_load_dwordx2 v[136:137], v[204:205], off
	global_load_dwordx2 v[138:139], v[206:207], off
	v_mul_f32_e32 v126, 0xbfb8aa3b, v126
	v_mul_f32_e32 v122, 0xbfb8aa3b, v122
	v_exp_f32_e32 v126, v126
	v_exp_f32_e32 v122, v122
	v_mul_f32_e32 v123, 0xbfb8aa3b, v123
	v_exp_f32_e32 v123, v123
	v_add_f32_e32 v126, 1.0, v126
	v_add_f32_e32 v122, 1.0, v122
	v_rcp_f32_e32 v206, v126
	v_mul_f32_e32 v126, 0xbfb8aa3b, v128
	v_rcp_f32_e32 v207, v122
	v_add_f32_e32 v122, 1.0, v123
	v_mul_f32_e32 v123, 0xbfb8aa3b, v124
	v_mul_f32_e32 v118, 0xbfb8aa3b, v118
	v_mul_f32_e32 v114, 0xbfb8aa3b, v114
	v_exp_f32_e32 v126, v126
	v_mul_f32_e32 v128, 0xbfb8aa3b, v129
	v_exp_f32_e32 v123, v123
	v_mul_f32_e32 v124, 0xbfb8aa3b, v125
	v_exp_f32_e32 v118, v118
	v_mul_f32_e32 v119, 0xbfb8aa3b, v119
	v_exp_f32_e32 v114, v114
	v_mul_f32_e32 v115, 0xbfb8aa3b, v115
	v_exp_f32_e32 v129, v128
	v_exp_f32_e32 v124, v124
	v_exp_f32_e32 v119, v119
	v_exp_f32_e32 v115, v115
	v_mul_f32_e32 v127, 0xbfb8aa3b, v127
	v_add_f32_e32 v126, 1.0, v126
	v_rcp_f32_e32 v205, v122
	v_add_f32_e32 v122, 1.0, v123
	v_add_f32_e32 v118, 1.0, v118
	v_add_f32_e32 v114, 1.0, v114
	v_exp_f32_e32 v127, v127
	v_rcp_f32_e32 v128, v126
	v_add_f32_e32 v126, 1.0, v129
	v_rcp_f32_e32 v129, v122
	v_add_f32_e32 v122, 1.0, v124
	v_rcp_f32_e32 v124, v118
	v_add_f32_e32 v118, 1.0, v119
	v_mul_f32_e32 v119, 0xbfb8aa3b, v120
	v_rcp_f32_e32 v125, v114
	v_add_f32_e32 v114, 1.0, v115
	v_mul_f32_e32 v115, 0xbfb8aa3b, v116
	v_mul_f32_e32 v110, 0xbfb8aa3b, v110
	v_mul_f32_e32 v106, 0xbfb8aa3b, v106
	v_exp_f32_e32 v119, v119
	v_mul_f32_e32 v120, 0xbfb8aa3b, v121
	v_exp_f32_e32 v115, v115
	v_mul_f32_e32 v116, 0xbfb8aa3b, v117
	v_exp_f32_e32 v110, v110
	v_mul_f32_e32 v111, 0xbfb8aa3b, v111
	v_exp_f32_e32 v106, v106
	v_mul_f32_e32 v107, 0xbfb8aa3b, v107
	v_exp_f32_e32 v121, v120
	v_exp_f32_e32 v116, v116
	v_exp_f32_e32 v111, v111
	v_exp_f32_e32 v107, v107
	v_add_f32_e32 v127, 1.0, v127
	v_rcp_f32_e32 v204, v127
	v_rcp_f32_e32 v127, v122
	v_rcp_f32_e32 v122, v118
	v_add_f32_e32 v118, 1.0, v119
	v_rcp_f32_e32 v123, v114
	v_add_f32_e32 v114, 1.0, v115
	v_add_f32_e32 v110, 1.0, v110
	v_add_f32_e32 v106, 1.0, v106
	v_rcp_f32_e32 v120, v118
	v_add_f32_e32 v118, 1.0, v121
	v_rcp_f32_e32 v121, v114
	v_add_f32_e32 v114, 1.0, v116
	v_rcp_f32_e32 v116, v110
	v_add_f32_e32 v110, 1.0, v111
	v_mul_f32_e32 v111, 0xbfb8aa3b, v112
	v_rcp_f32_e32 v117, v106
	v_add_f32_e32 v106, 1.0, v107
	v_mul_f32_e32 v107, 0xbfb8aa3b, v108
	v_exp_f32_e32 v111, v111
	v_mul_f32_e32 v112, 0xbfb8aa3b, v113
	v_exp_f32_e32 v107, v107
	v_mul_f32_e32 v108, 0xbfb8aa3b, v109
	v_mul_f32_e32 v102, 0xbfb8aa3b, v102
	v_exp_f32_e32 v113, v112
	v_exp_f32_e32 v108, v108
	v_exp_f32_e32 v102, v102
	v_mul_f32_e32 v103, 0xbfb8aa3b, v103
	v_exp_f32_e32 v103, v103
	v_rcp_f32_e32 v119, v114
	v_rcp_f32_e32 v114, v110
	v_add_f32_e32 v110, 1.0, v111
	v_rcp_f32_e32 v115, v106
	v_add_f32_e32 v106, 1.0, v107
	v_rcp_f32_e32 v112, v110
	v_add_f32_e32 v110, 1.0, v113
	v_rcp_f32_e32 v113, v106
	v_add_f32_e32 v106, 1.0, v108
	v_add_f32_e32 v102, 1.0, v102
	v_rcp_f32_e32 v111, v106
	v_rcp_f32_e32 v106, v102
	v_add_f32_e32 v102, 1.0, v103
	v_mul_f32_e32 v103, 0xbfb8aa3b, v104
	v_mul_f32_e32 v104, 0xbfb8aa3b, v105
	v_exp_f32_e32 v103, v103
	v_exp_f32_e32 v105, v104
	v_mul_f32_e32 v94, 0xbfb8aa3b, v94
	v_mul_f32_e32 v90, 0xbfb8aa3b, v90
	v_exp_f32_e32 v94, v94
	v_mul_f32_e32 v95, 0xbfb8aa3b, v95
	v_exp_f32_e32 v90, v90
	v_mul_f32_e32 v91, 0xbfb8aa3b, v91
	v_exp_f32_e32 v95, v95
	v_exp_f32_e32 v91, v91
	v_mul_f32_e32 v98, 0xbfb8aa3b, v98
	v_rcp_f32_e32 v104, v102
	v_add_f32_e32 v102, 1.0, v103
	v_add_f32_e32 v103, 1.0, v105
	v_exp_f32_e32 v105, v98
	v_mul_f32_e32 v98, 0xbfb8aa3b, v99
	v_exp_f32_e32 v99, v98
	v_mul_f32_e32 v100, 0xbfb8aa3b, v100
	v_add_f32_e32 v94, 1.0, v94
	v_add_f32_e32 v90, 1.0, v90
	v_exp_f32_e32 v100, v100
	v_mul_f32_e32 v101, 0xbfb8aa3b, v101
	v_rcp_f32_e32 v108, v94
	v_add_f32_e32 v94, 1.0, v95
	v_mul_f32_e32 v95, 0xbfb8aa3b, v96
	v_rcp_f32_e32 v109, v90
	v_add_f32_e32 v90, 1.0, v91
	v_mul_f32_e32 v91, 0xbfb8aa3b, v92
	v_mul_f32_e32 v86, 0xbfb8aa3b, v86
	v_mul_f32_e32 v82, 0xbfb8aa3b, v82
	v_exp_f32_e32 v101, v101
	v_exp_f32_e32 v95, v95
	v_mul_f32_e32 v96, 0xbfb8aa3b, v97
	v_exp_f32_e32 v91, v91
	v_mul_f32_e32 v92, 0xbfb8aa3b, v93
	v_exp_f32_e32 v86, v86
	v_mul_f32_e32 v87, 0xbfb8aa3b, v87
	v_exp_f32_e32 v82, v82
	v_mul_f32_e32 v83, 0xbfb8aa3b, v83
	v_exp_f32_e32 v97, v96
	v_exp_f32_e32 v92, v92
	v_exp_f32_e32 v87, v87
	v_exp_f32_e32 v83, v83
	v_add_f32_e32 v99, 1.0, v99
	v_rcp_f32_e32 v98, v103
	v_add_f32_e32 v103, 1.0, v105
	v_rcp_f32_e32 v105, v99
	v_add_f32_e32 v99, 1.0, v100
	v_rcp_f32_e32 v107, v103
	v_rcp_f32_e32 v103, v99
	v_add_f32_e32 v99, 1.0, v101
	v_rcp_f32_e32 v100, v94
	v_add_f32_e32 v94, 1.0, v95
	v_rcp_f32_e32 v101, v90
	v_add_f32_e32 v90, 1.0, v91
	v_add_f32_e32 v86, 1.0, v86
	v_add_f32_e32 v82, 1.0, v82
	v_rcp_f32_e32 v96, v94
	v_add_f32_e32 v94, 1.0, v97
	v_rcp_f32_e32 v97, v90
	v_add_f32_e32 v90, 1.0, v92
	v_rcp_f32_e32 v92, v86
	v_add_f32_e32 v86, 1.0, v87
	v_mul_f32_e32 v87, 0xbfb8aa3b, v88
	v_rcp_f32_e32 v93, v82
	v_add_f32_e32 v82, 1.0, v83
	v_mul_f32_e32 v83, 0xbfb8aa3b, v84
	v_mul_f32_e32 v78, 0xbfb8aa3b, v78
	v_mul_f32_e32 v74, 0xbfb8aa3b, v74
	v_exp_f32_e32 v87, v87
	v_mul_f32_e32 v88, 0xbfb8aa3b, v89
	v_exp_f32_e32 v83, v83
	v_mul_f32_e32 v84, 0xbfb8aa3b, v85
	v_exp_f32_e32 v78, v78
	v_mul_f32_e32 v79, 0xbfb8aa3b, v79
	v_exp_f32_e32 v74, v74
	v_mul_f32_e32 v75, 0xbfb8aa3b, v75
	v_exp_f32_e32 v89, v88
	v_exp_f32_e32 v84, v84
	v_exp_f32_e32 v79, v79
	v_exp_f32_e32 v75, v75
	v_rcp_f32_e32 v95, v90
	v_rcp_f32_e32 v90, v86
	v_add_f32_e32 v86, 1.0, v87
	v_rcp_f32_e32 v91, v82
	v_add_f32_e32 v82, 1.0, v83
	v_add_f32_e32 v78, 1.0, v78
	v_add_f32_e32 v74, 1.0, v74
	v_rcp_f32_e32 v88, v86
	v_add_f32_e32 v86, 1.0, v89
	v_rcp_f32_e32 v89, v82
	v_add_f32_e32 v82, 1.0, v84
	v_rcp_f32_e32 v84, v78
	v_add_f32_e32 v78, 1.0, v79
	v_mul_f32_e32 v79, 0xbfb8aa3b, v80
	v_rcp_f32_e32 v85, v74
	v_add_f32_e32 v74, 1.0, v75
	v_mul_f32_e32 v75, 0xbfb8aa3b, v76
	v_mul_f32_e32 v70, 0xbfb8aa3b, v70
	v_exp_f32_e32 v79, v79
	v_mul_f32_e32 v80, 0xbfb8aa3b, v81
	v_exp_f32_e32 v75, v75
	v_mul_f32_e32 v76, 0xbfb8aa3b, v77
	v_exp_f32_e32 v70, v70
	v_mul_f32_e32 v71, 0xbfb8aa3b, v71
	v_exp_f32_e32 v81, v80
	v_exp_f32_e32 v76, v76
	v_exp_f32_e32 v71, v71
	v_rcp_f32_e32 v87, v82
	v_rcp_f32_e32 v82, v78
	v_add_f32_e32 v78, 1.0, v79
	v_rcp_f32_e32 v83, v74
	v_add_f32_e32 v74, 1.0, v75
	v_add_f32_e32 v70, 1.0, v70
	v_rcp_f32_e32 v80, v78
	v_add_f32_e32 v78, 1.0, v81
	v_rcp_f32_e32 v81, v74
	v_add_f32_e32 v74, 1.0, v76
	v_rcp_f32_e32 v76, v70
	v_add_f32_e32 v70, 1.0, v71
	v_mul_f32_e32 v71, 0xbfb8aa3b, v72
	v_mul_f32_e32 v72, 0xbfb8aa3b, v73
	v_exp_f32_e32 v71, v71
	v_exp_f32_e32 v72, v72
	v_mul_f32_e32 v62, 0xbfb8aa3b, v62
	v_mul_f32_e32 v58, 0xbfb8aa3b, v58
	v_mul_f32_e32 v66, 0xbfb8aa3b, v66
	v_exp_f32_e32 v62, v62
	v_mul_f32_e32 v63, 0xbfb8aa3b, v63
	v_exp_f32_e32 v58, v58
	v_mul_f32_e32 v59, 0xbfb8aa3b, v59
	v_rcp_f32_e32 v79, v74
	v_rcp_f32_e32 v74, v70
	v_add_f32_e32 v70, 1.0, v71
	v_add_f32_e32 v71, 1.0, v72
	v_exp_f32_e32 v72, v66
	v_exp_f32_e32 v63, v63
	v_exp_f32_e32 v59, v59
	v_mul_f32_e32 v66, 0xbfb8aa3b, v67
	v_exp_f32_e32 v67, v66
	v_mul_f32_e32 v68, 0xbfb8aa3b, v68
	v_add_f32_e32 v62, 1.0, v62
	v_add_f32_e32 v58, 1.0, v58
	v_rcp_f32_e32 v66, v71
	v_add_f32_e32 v71, 1.0, v72
	v_exp_f32_e32 v68, v68
	v_mul_f32_e32 v69, 0xbfb8aa3b, v69
	v_rcp_f32_e32 v72, v62
	v_add_f32_e32 v62, 1.0, v63
	v_mul_f32_e32 v63, 0xbfb8aa3b, v64
	v_rcp_f32_e32 v73, v58
	v_add_f32_e32 v58, 1.0, v59
	v_mul_f32_e32 v59, 0xbfb8aa3b, v60
	v_mul_f32_e32 v54, 0xbfb8aa3b, v54
	v_mul_f32_e32 v50, 0xbfb8aa3b, v50
	v_exp_f32_e32 v69, v69
	v_exp_f32_e32 v63, v63
	v_mul_f32_e32 v64, 0xbfb8aa3b, v65
	v_exp_f32_e32 v59, v59
	v_mul_f32_e32 v60, 0xbfb8aa3b, v61
	v_exp_f32_e32 v54, v54
	v_mul_f32_e32 v55, 0xbfb8aa3b, v55
	v_exp_f32_e32 v50, v50
	v_mul_f32_e32 v51, 0xbfb8aa3b, v51
	v_exp_f32_e32 v65, v64
	v_exp_f32_e32 v60, v60
	v_exp_f32_e32 v55, v55
	v_exp_f32_e32 v51, v51
	v_add_f32_e32 v67, 1.0, v67
	v_rcp_f32_e32 v75, v67
	v_add_f32_e32 v67, 1.0, v68
	v_rcp_f32_e32 v77, v71
	v_rcp_f32_e32 v71, v67
	v_add_f32_e32 v67, 1.0, v69
	v_rcp_f32_e32 v68, v62
	v_add_f32_e32 v62, 1.0, v63
	v_rcp_f32_e32 v69, v58
	v_add_f32_e32 v58, 1.0, v59
	v_add_f32_e32 v54, 1.0, v54
	v_add_f32_e32 v50, 1.0, v50
	v_rcp_f32_e32 v64, v62
	v_add_f32_e32 v62, 1.0, v65
	v_rcp_f32_e32 v65, v58
	v_add_f32_e32 v58, 1.0, v60
	v_rcp_f32_e32 v60, v54
	v_add_f32_e32 v54, 1.0, v55
	v_mul_f32_e32 v55, 0xbfb8aa3b, v56
	v_rcp_f32_e32 v61, v50
	v_add_f32_e32 v50, 1.0, v51
	v_mul_f32_e32 v51, 0xbfb8aa3b, v52
	v_mul_f32_e32 v46, 0xbfb8aa3b, v46
	v_mul_f32_e32 v42, 0xbfb8aa3b, v42
	v_exp_f32_e32 v55, v55
	v_mul_f32_e32 v56, 0xbfb8aa3b, v57
	v_exp_f32_e32 v51, v51
	v_mul_f32_e32 v52, 0xbfb8aa3b, v53
	v_exp_f32_e32 v46, v46
	v_mul_f32_e32 v47, 0xbfb8aa3b, v47
	v_exp_f32_e32 v42, v42
	v_mul_f32_e32 v43, 0xbfb8aa3b, v43
	v_exp_f32_e32 v57, v56
	v_exp_f32_e32 v52, v52
	v_exp_f32_e32 v47, v47
	v_exp_f32_e32 v43, v43
	v_rcp_f32_e32 v63, v58
	v_rcp_f32_e32 v58, v54
	v_add_f32_e32 v54, 1.0, v55
	v_rcp_f32_e32 v59, v50
	v_add_f32_e32 v50, 1.0, v51
	v_add_f32_e32 v46, 1.0, v46
	v_add_f32_e32 v42, 1.0, v42
	v_rcp_f32_e32 v56, v54
	v_add_f32_e32 v54, 1.0, v57
	v_rcp_f32_e32 v57, v50
	v_add_f32_e32 v50, 1.0, v52
	v_rcp_f32_e32 v52, v46
	v_add_f32_e32 v46, 1.0, v47
	v_mul_f32_e32 v47, 0xbfb8aa3b, v48
	v_rcp_f32_e32 v53, v42
	v_add_f32_e32 v42, 1.0, v43
	v_mul_f32_e32 v43, 0xbfb8aa3b, v44
	v_exp_f32_e32 v47, v47
	v_mul_f32_e32 v48, 0xbfb8aa3b, v49
	v_exp_f32_e32 v43, v43
	v_mul_f32_e32 v44, 0xbfb8aa3b, v45
	v_mul_f32_e32 v38, 0xbfb8aa3b, v38
	v_exp_f32_e32 v49, v48
	v_exp_f32_e32 v44, v44
	v_exp_f32_e32 v38, v38
	v_mul_f32_e32 v39, 0xbfb8aa3b, v39
	v_exp_f32_e32 v39, v39
	v_rcp_f32_e32 v55, v50
	v_rcp_f32_e32 v50, v46
	v_add_f32_e32 v46, 1.0, v47
	v_rcp_f32_e32 v51, v42
	v_add_f32_e32 v42, 1.0, v43
	v_rcp_f32_e32 v48, v46
	v_add_f32_e32 v46, 1.0, v49
	v_rcp_f32_e32 v49, v42
	v_add_f32_e32 v42, 1.0, v44
	v_add_f32_e32 v38, 1.0, v38
	v_rcp_f32_e32 v47, v42
	v_rcp_f32_e32 v42, v38
	v_add_f32_e32 v38, 1.0, v39
	v_mul_f32_e32 v39, 0xbfb8aa3b, v40
	v_mul_f32_e32 v40, 0xbfb8aa3b, v41
	v_exp_f32_e32 v39, v39
	v_exp_f32_e32 v41, v40
	v_mul_f32_e32 v30, 0xbfb8aa3b, v30
	v_mul_f32_e32 v26, 0xbfb8aa3b, v26
	v_exp_f32_e32 v30, v30
	v_mul_f32_e32 v31, 0xbfb8aa3b, v31
	v_exp_f32_e32 v26, v26
	v_mul_f32_e32 v27, 0xbfb8aa3b, v27
	v_exp_f32_e32 v31, v31
	v_exp_f32_e32 v27, v27
	v_mul_f32_e32 v34, 0xbfb8aa3b, v34
	v_rcp_f32_e32 v40, v38
	v_add_f32_e32 v38, 1.0, v39
	v_add_f32_e32 v39, 1.0, v41
	v_exp_f32_e32 v41, v34
	v_mul_f32_e32 v34, 0xbfb8aa3b, v35
	v_exp_f32_e32 v35, v34
	v_mul_f32_e32 v36, 0xbfb8aa3b, v36
	v_add_f32_e32 v30, 1.0, v30
	v_add_f32_e32 v26, 1.0, v26
	v_exp_f32_e32 v36, v36
	v_mul_f32_e32 v37, 0xbfb8aa3b, v37
	v_rcp_f32_e32 v44, v30
	v_add_f32_e32 v30, 1.0, v31
	v_mul_f32_e32 v31, 0xbfb8aa3b, v32
	v_rcp_f32_e32 v45, v26
	v_add_f32_e32 v26, 1.0, v27
	v_mul_f32_e32 v27, 0xbfb8aa3b, v28
	v_mul_f32_e32 v22, 0xbfb8aa3b, v22
	v_mul_f32_e32 v18, 0xbfb8aa3b, v18
	v_exp_f32_e32 v37, v37
	v_exp_f32_e32 v31, v31
	v_mul_f32_e32 v32, 0xbfb8aa3b, v33
	v_exp_f32_e32 v27, v27
	v_mul_f32_e32 v28, 0xbfb8aa3b, v29
	v_exp_f32_e32 v22, v22
	v_mul_f32_e32 v23, 0xbfb8aa3b, v23
	v_exp_f32_e32 v18, v18
	v_mul_f32_e32 v19, 0xbfb8aa3b, v19
	v_exp_f32_e32 v33, v32
	v_exp_f32_e32 v28, v28
	v_exp_f32_e32 v23, v23
	v_exp_f32_e32 v19, v19
	v_add_f32_e32 v35, 1.0, v35
	v_rcp_f32_e32 v34, v39
	v_add_f32_e32 v39, 1.0, v41
	v_rcp_f32_e32 v41, v35
	v_add_f32_e32 v35, 1.0, v36
	v_rcp_f32_e32 v43, v39
	v_rcp_f32_e32 v39, v35
	v_add_f32_e32 v35, 1.0, v37
	v_rcp_f32_e32 v36, v30
	v_add_f32_e32 v30, 1.0, v31
	v_rcp_f32_e32 v37, v26
	v_add_f32_e32 v26, 1.0, v27
	v_add_f32_e32 v22, 1.0, v22
	v_add_f32_e32 v18, 1.0, v18
	v_rcp_f32_e32 v32, v30
	v_add_f32_e32 v30, 1.0, v33
	v_rcp_f32_e32 v33, v26
	v_add_f32_e32 v26, 1.0, v28
	v_rcp_f32_e32 v28, v22
	v_add_f32_e32 v22, 1.0, v23
	v_mul_f32_e32 v23, 0xbfb8aa3b, v24
	v_rcp_f32_e32 v29, v18
	v_add_f32_e32 v18, 1.0, v19
	v_mul_f32_e32 v19, 0xbfb8aa3b, v20
	v_mul_f32_e32 v12, 0xbfb8aa3b, v12
	v_mul_f32_e32 v8, 0xbfb8aa3b, v8
	v_exp_f32_e32 v23, v23
	v_mul_f32_e32 v24, 0xbfb8aa3b, v25
	v_exp_f32_e32 v19, v19
	v_mul_f32_e32 v20, 0xbfb8aa3b, v21
	v_exp_f32_e32 v12, v12
	v_mul_f32_e32 v13, 0xbfb8aa3b, v13
	v_exp_f32_e32 v8, v8
	v_mul_f32_e32 v9, 0xbfb8aa3b, v9
	v_exp_f32_e32 v25, v24
	v_exp_f32_e32 v20, v20
	v_exp_f32_e32 v13, v13
	v_exp_f32_e32 v9, v9
	v_rcp_f32_e32 v31, v26
	v_rcp_f32_e32 v26, v22
	v_add_f32_e32 v22, 1.0, v23
	v_rcp_f32_e32 v27, v18
	v_add_f32_e32 v18, 1.0, v19
	v_add_f32_e32 v12, 1.0, v12
	v_add_f32_e32 v8, 1.0, v8
	v_rcp_f32_e32 v24, v22
	v_add_f32_e32 v22, 1.0, v25
	v_rcp_f32_e32 v25, v18
	v_add_f32_e32 v18, 1.0, v20
	v_rcp_f32_e32 v20, v12
	v_add_f32_e32 v12, 1.0, v13
	v_mul_f32_e32 v13, 0xbfb8aa3b, v14
	v_rcp_f32_e32 v21, v8
	v_add_f32_e32 v8, 1.0, v9
	v_mul_f32_e32 v9, 0xbfb8aa3b, v10
	v_exp_f32_e32 v13, v13
	v_mul_f32_e32 v14, 0xbfb8aa3b, v15
	v_exp_f32_e32 v9, v9
	v_mul_f32_e32 v10, 0xbfb8aa3b, v11
	v_mul_f32_e32 v4, 0xbfb8aa3b, v4
	v_exp_f32_e32 v15, v14
	v_exp_f32_e32 v10, v10
	v_exp_f32_e32 v4, v4
	v_mul_f32_e32 v5, 0xbfb8aa3b, v5
	v_exp_f32_e32 v5, v5
	v_rcp_f32_e32 v23, v18
	v_rcp_f32_e32 v18, v12
	v_add_f32_e32 v12, 1.0, v13
	v_rcp_f32_e32 v19, v8
	v_add_f32_e32 v8, 1.0, v9
	v_rcp_f32_e32 v14, v12
	v_add_f32_e32 v12, 1.0, v15
	v_rcp_f32_e32 v15, v8
	v_add_f32_e32 v8, 1.0, v10
	v_add_f32_e32 v4, 1.0, v4
	v_rcp_f32_e32 v13, v8
	v_rcp_f32_e32 v8, v4
	v_add_f32_e32 v4, 1.0, v5
	v_mul_f32_e32 v5, 0xbfb8aa3b, v6
	v_mul_f32_e32 v6, 0xbfb8aa3b, v7
	v_exp_f32_e32 v5, v5
	v_exp_f32_e32 v7, v6
	v_mul_f32_e32 v0, 0xbfb8aa3b, v0
	v_rcp_f32_e32 v6, v4
	v_add_f32_e32 v4, 1.0, v5
	v_add_f32_e32 v5, 1.0, v7
	v_exp_f32_e32 v7, v0
	v_mul_f32_e32 v0, 0xbfb8aa3b, v1
	v_exp_f32_e32 v1, v0
	v_mul_f32_e32 v2, 0xbfb8aa3b, v2
	v_exp_f32_e32 v2, v2
	v_mul_f32_e32 v3, 0xbfb8aa3b, v3
	v_exp_f32_e32 v3, v3
	v_add_f32_e32 v1, 1.0, v1
	v_rcp_f32_e32 v0, v5
	v_add_f32_e32 v5, 1.0, v7
	v_rcp_f32_e32 v7, v1
	v_add_f32_e32 v1, 1.0, v2
	v_rcp_f32_e32 v9, v5
	v_rcp_f32_e32 v5, v1
	v_add_f32_e32 v1, 1.0, v3
	v_rcp_f32_e32 v126, v126
	v_rcp_f32_e32 v118, v118
	v_rcp_f32_e32 v110, v110
	v_rcp_f32_e32 v102, v102
	v_rcp_f32_e32 v99, v99
	v_rcp_f32_e32 v94, v94
	v_rcp_f32_e32 v86, v86
	v_rcp_f32_e32 v78, v78
	v_rcp_f32_e32 v70, v70
	v_rcp_f32_e32 v67, v67
	v_rcp_f32_e32 v62, v62
	v_rcp_f32_e32 v54, v54
	v_rcp_f32_e32 v46, v46
	v_rcp_f32_e32 v38, v38
	v_rcp_f32_e32 v35, v35
	v_rcp_f32_e32 v30, v30
	v_rcp_f32_e32 v22, v22
	v_rcp_f32_e32 v12, v12
	v_rcp_f32_e32 v4, v4
	v_rcp_f32_e32 v1, v1
	s_waitcnt vmcnt(0)
	v_lshlrev_b32_e32 v3, 16, v202
	v_lshlrev_b32_e32 v2, 16, v200
	v_pk_mul_f32 v[2:3], v[206:207], v[2:3]
	s_mov_b64 s[28:29], -1
	v_add_f32_e32 v2, 0, v2
	v_add_f32_e32 v10, v2, v3
	v_and_b32_e32 v3, 0xffff0000, v202
	v_and_b32_e32 v2, 0xffff0000, v200
	v_pk_mul_f32 v[2:3], v[204:205], v[2:3]
	s_mov_b64 s[92:93], 0x2000
	v_add_f32_e32 v2, 0, v2
	v_add_f32_e32 v11, v2, v3
	v_lshlrev_b32_e32 v3, 16, v203
	v_lshlrev_b32_e32 v2, 16, v201
	v_pk_mul_f32 v[2:3], v[128:129], v[2:3]
	s_mov_b64 s[90:91], s[62:63]
	v_add_f32_e32 v2, 0, v2
	v_add_f32_e32 v128, v2, v3
	v_and_b32_e32 v3, 0xffff0000, v203
	v_and_b32_e32 v2, 0xffff0000, v201
	v_pk_mul_f32 v[2:3], v[126:127], v[2:3]
	s_nop 0
	v_add_f32_e32 v2, 0, v2
	v_add_f32_e32 v126, v2, v3
	v_lshlrev_b32_e32 v3, 16, v198
	v_lshlrev_b32_e32 v2, 16, v196
	v_pk_mul_f32 v[2:3], v[108:109], v[2:3]
	s_nop 0
	v_add_f32_e32 v2, v10, v2
	v_add_f32_e32 v10, v2, v3
	v_and_b32_e32 v3, 0xffff0000, v198
	v_and_b32_e32 v2, 0xffff0000, v196
	v_pk_mul_f32 v[2:3], v[100:101], v[2:3]
	s_nop 0
	v_add_f32_e32 v2, v11, v2
	v_add_f32_e32 v11, v2, v3
	v_lshlrev_b32_e32 v3, 16, v199
	v_lshlrev_b32_e32 v2, 16, v197
	v_pk_mul_f32 v[2:3], v[96:97], v[2:3]
	v_cvt_pk_bf16_f32 v10, v10, v11
	s_nop 0
	v_add_f32_e32 v2, v128, v2
	v_add_f32_e32 v96, v2, v3
	v_and_b32_e32 v3, 0xffff0000, v199
	v_and_b32_e32 v2, 0xffff0000, v197
	v_pk_mul_f32 v[2:3], v[94:95], v[2:3]
	v_lshlrev_b32_e32 v95, 16, v194
	v_add_f32_e32 v2, v126, v2
	v_add_f32_e32 v2, v2, v3
	v_cvt_pk_bf16_f32 v11, v96, v2
	v_lshlrev_b64 v[2:3], 12, v[162:163]
	v_lshl_add_u64 v[2:3], s[72:73], 0, v[2:3]
	v_lshlrev_b32_e32 v94, 16, v192
	v_lshl_add_u64 v[2:3], v[2:3], 0, v[148:149]
	v_pk_mul_f32 v[94:95], v[124:125], v[94:95]
	global_store_dwordx2 v[2:3], v[10:11], off
	v_add_f32_e32 v11, 0, v94
	v_add_f32_e32 v11, v11, v95
	v_and_b32_e32 v95, 0xffff0000, v194
	v_and_b32_e32 v94, 0xffff0000, v192
	v_pk_mul_f32 v[94:95], v[122:123], v[94:95]
	v_or_b32_e32 v10, 16, v162
	v_add_f32_e32 v94, 0, v94
	v_add_f32_e32 v96, v94, v95
	v_lshlrev_b32_e32 v95, 16, v195
	v_lshlrev_b32_e32 v94, 16, v193
	v_pk_mul_f32 v[94:95], v[120:121], v[94:95]
	s_nop 0
	v_add_f32_e32 v94, 0, v94
	v_add_f32_e32 v97, v94, v95
	v_and_b32_e32 v95, 0xffff0000, v195
	v_and_b32_e32 v94, 0xffff0000, v193
	v_pk_mul_f32 v[94:95], v[118:119], v[94:95]
	s_nop 0
	v_add_f32_e32 v94, 0, v94
	v_add_f32_e32 v100, v94, v95
	v_lshlrev_b32_e32 v95, 16, v190
	v_lshlrev_b32_e32 v94, 16, v188
	v_pk_mul_f32 v[92:93], v[92:93], v[94:95]
	s_nop 0
	v_add_f32_e32 v11, v11, v92
	v_add_f32_e32 v94, v11, v93
	v_and_b32_e32 v93, 0xffff0000, v190
	v_and_b32_e32 v92, 0xffff0000, v188
	v_pk_mul_f32 v[90:91], v[90:91], v[92:93]
	s_nop 0
	v_add_f32_e32 v11, v96, v90
	v_add_f32_e32 v92, v11, v91
	v_lshlrev_b32_e32 v91, 16, v191
	v_lshlrev_b32_e32 v90, 16, v189
	v_pk_mul_f32 v[88:89], v[88:89], v[90:91]
	s_nop 0
	v_add_f32_e32 v11, v97, v88
	v_add_f32_e32 v90, v11, v89
	v_and_b32_e32 v89, 0xffff0000, v191
	v_and_b32_e32 v88, 0xffff0000, v189
	v_pk_mul_f32 v[86:87], v[86:87], v[88:89]
	s_nop 0
	v_add_f32_e32 v11, v100, v86
	v_add_f32_e32 v87, v11, v87
	v_ashrrev_i32_e32 v11, 31, v10
	v_lshlrev_b64 v[10:11], 12, v[10:11]
	v_lshl_add_u64 v[10:11], s[72:73], 0, v[10:11]
	v_cvt_pk_bf16_f32 v86, v94, v92
	v_cvt_pk_bf16_f32 v87, v90, v87
	v_lshl_add_u64 v[10:11], v[10:11], 0, v[148:149]
	global_store_dwordx2 v[10:11], v[86:87], off
	v_lshlrev_b32_e32 v87, 16, v186
	v_lshlrev_b32_e32 v86, 16, v184
	v_pk_mul_f32 v[86:87], v[116:117], v[86:87]
	v_or_b32_e32 v10, 32, v162
	v_add_f32_e32 v11, 0, v86
	v_add_f32_e32 v11, v11, v87
	v_and_b32_e32 v87, 0xffff0000, v186
	v_and_b32_e32 v86, 0xffff0000, v184
	v_pk_mul_f32 v[86:87], v[114:115], v[86:87]
	s_nop 0
	v_add_f32_e32 v86, 0, v86
	v_add_f32_e32 v88, v86, v87
	v_lshlrev_b32_e32 v87, 16, v187
	v_lshlrev_b32_e32 v86, 16, v185
	v_pk_mul_f32 v[86:87], v[112:113], v[86:87]
	s_nop 0
	v_add_f32_e32 v86, 0, v86
	v_add_f32_e32 v89, v86, v87
	v_and_b32_e32 v87, 0xffff0000, v187
	v_and_b32_e32 v86, 0xffff0000, v185
	v_pk_mul_f32 v[86:87], v[110:111], v[86:87]
	s_nop 0
	v_add_f32_e32 v86, 0, v86
	v_add_f32_e32 v90, v86, v87
	v_lshlrev_b32_e32 v87, 16, v182
	v_lshlrev_b32_e32 v86, 16, v180
	v_pk_mul_f32 v[84:85], v[84:85], v[86:87]
	s_nop 0
	v_add_f32_e32 v11, v11, v84
	v_add_f32_e32 v86, v11, v85
	v_and_b32_e32 v85, 0xffff0000, v182
	v_and_b32_e32 v84, 0xffff0000, v180
	v_pk_mul_f32 v[82:83], v[82:83], v[84:85]
	s_nop 0
	v_add_f32_e32 v11, v88, v82
	v_add_f32_e32 v84, v11, v83
	v_lshlrev_b32_e32 v83, 16, v183
	v_lshlrev_b32_e32 v82, 16, v181
	v_pk_mul_f32 v[80:81], v[80:81], v[82:83]
	s_nop 0
	v_add_f32_e32 v11, v89, v80
	v_add_f32_e32 v82, v11, v81
	v_and_b32_e32 v81, 0xffff0000, v183
	v_and_b32_e32 v80, 0xffff0000, v181
	v_pk_mul_f32 v[78:79], v[78:79], v[80:81]
	s_nop 0
	v_add_f32_e32 v11, v90, v78
	v_add_f32_e32 v79, v11, v79
	v_ashrrev_i32_e32 v11, 31, v10
	v_lshlrev_b64 v[10:11], 12, v[10:11]
	v_lshl_add_u64 v[10:11], s[72:73], 0, v[10:11]
	v_cvt_pk_bf16_f32 v78, v86, v84
	v_cvt_pk_bf16_f32 v79, v82, v79
	v_lshl_add_u64 v[10:11], v[10:11], 0, v[148:149]
	global_store_dwordx2 v[10:11], v[78:79], off
	v_lshlrev_b32_e32 v79, 16, v178
	v_lshlrev_b32_e32 v78, 16, v176
	v_pk_mul_f32 v[78:79], v[106:107], v[78:79]
	v_or_b32_e32 v10, 48, v162
	v_add_f32_e32 v11, 0, v78
	v_add_f32_e32 v11, v11, v79
	v_and_b32_e32 v79, 0xffff0000, v178
	v_and_b32_e32 v78, 0xffff0000, v176
	v_pk_mul_f32 v[78:79], v[104:105], v[78:79]
	s_nop 0
	v_add_f32_e32 v78, 0, v78
	v_add_f32_e32 v80, v78, v79
	v_lshlrev_b32_e32 v79, 16, v179
	v_lshlrev_b32_e32 v78, 16, v177
	v_pk_mul_f32 v[78:79], v[102:103], v[78:79]
	s_nop 0
	v_add_f32_e32 v78, 0, v78
	v_add_f32_e32 v81, v78, v79
	v_and_b32_e32 v79, 0xffff0000, v179
	v_and_b32_e32 v78, 0xffff0000, v177
	v_pk_mul_f32 v[78:79], v[98:99], v[78:79]
	s_nop 0
	v_add_f32_e32 v78, 0, v78
	v_add_f32_e32 v82, v78, v79
	v_lshlrev_b32_e32 v79, 16, v174
	v_lshlrev_b32_e32 v78, 16, v172
	v_pk_mul_f32 v[76:77], v[76:77], v[78:79]
	s_nop 0
	v_add_f32_e32 v11, v11, v76
	v_add_f32_e32 v78, v11, v77
	v_and_b32_e32 v77, 0xffff0000, v174
	v_and_b32_e32 v76, 0xffff0000, v172
	v_pk_mul_f32 v[74:75], v[74:75], v[76:77]
	s_nop 0
	v_add_f32_e32 v11, v80, v74
	v_add_f32_e32 v76, v11, v75
	v_lshlrev_b32_e32 v75, 16, v175
	v_lshlrev_b32_e32 v74, 16, v173
	v_pk_mul_f32 v[70:71], v[70:71], v[74:75]
	s_nop 0
	v_add_f32_e32 v11, v81, v70
	v_add_f32_e32 v74, v11, v71
	v_and_b32_e32 v71, 0xffff0000, v175
	v_and_b32_e32 v70, 0xffff0000, v173
	v_pk_mul_f32 v[66:67], v[66:67], v[70:71]
	s_nop 0
	v_add_f32_e32 v11, v82, v66
	v_add_f32_e32 v67, v11, v67
	v_ashrrev_i32_e32 v11, 31, v10
	v_lshlrev_b64 v[10:11], 12, v[10:11]
	v_lshl_add_u64 v[10:11], s[72:73], 0, v[10:11]
	v_lshl_add_u64 v[10:11], v[10:11], 0, v[148:149]
	v_cvt_pk_bf16_f32 v66, v78, v76
	v_cvt_pk_bf16_f32 v67, v74, v67
	global_store_dwordx2 v[10:11], v[66:67], off
	v_lshlrev_b32_e32 v11, 16, v170
	v_lshlrev_b32_e32 v10, 16, v168
	v_pk_mul_f32 v[10:11], v[72:73], v[10:11]
	s_nop 0
	v_add_f32_e32 v10, 0, v10
	v_add_f32_e32 v66, v10, v11
	v_and_b32_e32 v11, 0xffff0000, v170
	v_and_b32_e32 v10, 0xffff0000, v168
	v_pk_mul_f32 v[10:11], v[68:69], v[10:11]
	s_nop 0
	v_add_f32_e32 v10, 0, v10
	v_add_f32_e32 v67, v10, v11
	v_lshlrev_b32_e32 v11, 16, v171
	v_lshlrev_b32_e32 v10, 16, v169
	v_pk_mul_f32 v[10:11], v[64:65], v[10:11]
	s_nop 0
	v_add_f32_e32 v10, 0, v10
	v_add_f32_e32 v64, v10, v11
	v_and_b32_e32 v11, 0xffff0000, v171
	v_and_b32_e32 v10, 0xffff0000, v169
	v_pk_mul_f32 v[10:11], v[62:63], v[10:11]
	s_nop 0
	v_add_f32_e32 v10, 0, v10
	v_add_f32_e32 v62, v10, v11
	v_lshlrev_b32_e32 v11, 16, v166
	v_lshlrev_b32_e32 v10, 16, v164
	v_pk_mul_f32 v[10:11], v[44:45], v[10:11]
	s_nop 0
	v_add_f32_e32 v10, v66, v10
	v_add_f32_e32 v44, v10, v11
	v_and_b32_e32 v11, 0xffff0000, v166
	v_and_b32_e32 v10, 0xffff0000, v164
	v_pk_mul_f32 v[10:11], v[36:37], v[10:11]
	s_nop 0
	v_add_f32_e32 v10, v67, v10
	v_add_f32_e32 v36, v10, v11
	v_lshlrev_b32_e32 v11, 16, v167
	v_lshlrev_b32_e32 v10, 16, v165
	v_pk_mul_f32 v[10:11], v[32:33], v[10:11]
	s_nop 0
	v_add_f32_e32 v10, v64, v10
	v_add_f32_e32 v32, v10, v11
	v_and_b32_e32 v11, 0xffff0000, v167
	v_and_b32_e32 v10, 0xffff0000, v165
	v_pk_mul_f32 v[10:11], v[30:31], v[10:11]
	v_add_co_u32_e32 v30, vcc, s64, v2
	v_add_f32_e32 v10, v62, v10
	v_add_f32_e32 v11, v10, v11
	v_cvt_pk_bf16_f32 v10, v44, v36
	v_cvt_pk_bf16_f32 v11, v32, v11
	v_addc_co_u32_e32 v31, vcc, 0, v3, vcc
	global_store_dwordx2 v[30:31], v[10:11], off
	v_lshlrev_b32_e32 v11, 16, v160
	v_lshlrev_b32_e32 v10, 16, v158
	v_pk_mul_f32 v[10:11], v[60:61], v[10:11]
	s_nop 0
	v_add_f32_e32 v10, 0, v10
	v_add_f32_e32 v30, v10, v11
	v_and_b32_e32 v11, 0xffff0000, v160
	v_and_b32_e32 v10, 0xffff0000, v158
	v_pk_mul_f32 v[10:11], v[58:59], v[10:11]
	s_nop 0
	v_add_f32_e32 v10, 0, v10
	v_add_f32_e32 v31, v10, v11
	v_lshlrev_b32_e32 v11, 16, v161
	v_lshlrev_b32_e32 v10, 16, v159
	v_pk_mul_f32 v[10:11], v[56:57], v[10:11]
	s_nop 0
	v_add_f32_e32 v10, 0, v10
	v_add_f32_e32 v32, v10, v11
	v_and_b32_e32 v11, 0xffff0000, v161
	v_and_b32_e32 v10, 0xffff0000, v159
	v_pk_mul_f32 v[10:11], v[54:55], v[10:11]
	s_nop 0
	v_add_f32_e32 v10, 0, v10
	v_add_f32_e32 v33, v10, v11
	v_lshlrev_b32_e32 v11, 16, v156
	v_lshlrev_b32_e32 v10, 16, v154
	v_pk_mul_f32 v[10:11], v[28:29], v[10:11]
	s_nop 0
	v_add_f32_e32 v10, v30, v10
	v_add_f32_e32 v28, v10, v11
	v_and_b32_e32 v11, 0xffff0000, v156
	v_and_b32_e32 v10, 0xffff0000, v154
	v_pk_mul_f32 v[10:11], v[26:27], v[10:11]
	s_nop 0
	v_add_f32_e32 v10, v31, v10
	v_add_f32_e32 v26, v10, v11
	v_lshlrev_b32_e32 v11, 16, v157
	v_lshlrev_b32_e32 v10, 16, v155
	v_pk_mul_f32 v[10:11], v[24:25], v[10:11]
	s_nop 0
	v_add_f32_e32 v10, v32, v10
	v_add_f32_e32 v24, v10, v11
	v_and_b32_e32 v11, 0xffff0000, v157
	v_and_b32_e32 v10, 0xffff0000, v155
	v_pk_mul_f32 v[10:11], v[22:23], v[10:11]
	v_add_co_u32_e32 v22, vcc, s31, v2
	v_add_f32_e32 v10, v33, v10
	v_add_f32_e32 v11, v10, v11
	v_cvt_pk_bf16_f32 v10, v28, v26
	v_cvt_pk_bf16_f32 v11, v24, v11
	v_addc_co_u32_e32 v23, vcc, 0, v3, vcc
	global_store_dwordx2 v[22:23], v[10:11], off
	v_lshlrev_b32_e32 v11, 16, v152
	v_lshlrev_b32_e32 v10, 16, v150
	v_pk_mul_f32 v[10:11], v[52:53], v[10:11]
	s_nop 0
	v_add_f32_e32 v10, 0, v10
	v_add_f32_e32 v22, v10, v11
	v_and_b32_e32 v11, 0xffff0000, v152
	v_and_b32_e32 v10, 0xffff0000, v150
	v_pk_mul_f32 v[10:11], v[50:51], v[10:11]
	s_nop 0
	v_add_f32_e32 v10, 0, v10
	v_add_f32_e32 v23, v10, v11
	v_lshlrev_b32_e32 v11, 16, v153
	v_lshlrev_b32_e32 v10, 16, v151
	v_pk_mul_f32 v[10:11], v[48:49], v[10:11]
	s_nop 0
	v_add_f32_e32 v10, 0, v10
	v_add_f32_e32 v24, v10, v11
	v_and_b32_e32 v11, 0xffff0000, v153
	v_and_b32_e32 v10, 0xffff0000, v151
	v_pk_mul_f32 v[10:11], v[46:47], v[10:11]
	s_nop 0
	v_add_f32_e32 v10, 0, v10
	v_add_f32_e32 v25, v10, v11
	v_lshlrev_b32_e32 v11, 16, v146
	v_lshlrev_b32_e32 v10, 16, v144
	v_pk_mul_f32 v[10:11], v[20:21], v[10:11]
	s_nop 0
	v_add_f32_e32 v10, v22, v10
	v_add_f32_e32 v20, v10, v11
	v_and_b32_e32 v11, 0xffff0000, v146
	v_and_b32_e32 v10, 0xffff0000, v144
	v_pk_mul_f32 v[10:11], v[18:19], v[10:11]
	s_nop 0
	v_add_f32_e32 v10, v23, v10
	v_add_f32_e32 v18, v10, v11
	v_lshlrev_b32_e32 v11, 16, v147
	v_lshlrev_b32_e32 v10, 16, v145
	v_pk_mul_f32 v[10:11], v[14:15], v[10:11]
	s_nop 0
	v_add_f32_e32 v10, v24, v10
	v_add_f32_e32 v14, v10, v11
	v_and_b32_e32 v11, 0xffff0000, v147
	v_and_b32_e32 v10, 0xffff0000, v145
	v_pk_mul_f32 v[10:11], v[12:13], v[10:11]
	v_add_co_u32_e32 v12, vcc, s65, v2
	v_add_f32_e32 v10, v25, v10
	v_add_f32_e32 v11, v10, v11
	v_cvt_pk_bf16_f32 v10, v20, v18
	v_cvt_pk_bf16_f32 v11, v14, v11
	v_addc_co_u32_e32 v13, vcc, 0, v3, vcc
	global_store_dwordx2 v[12:13], v[10:11], off
	v_lshlrev_b32_e32 v11, 16, v142
	v_lshlrev_b32_e32 v10, 16, v140
	v_pk_mul_f32 v[10:11], v[42:43], v[10:11]
	v_add_co_u32_e32 v2, vcc, 0xb0000, v2
	v_add_f32_e32 v10, 0, v10
	v_add_f32_e32 v12, v10, v11
	v_and_b32_e32 v11, 0xffff0000, v142
	v_and_b32_e32 v10, 0xffff0000, v140
	v_pk_mul_f32 v[10:11], v[40:41], v[10:11]
	v_addc_co_u32_e32 v3, vcc, 0, v3, vcc
	v_add_f32_e32 v10, 0, v10
	v_add_f32_e32 v13, v10, v11
	v_lshlrev_b32_e32 v11, 16, v143
	v_lshlrev_b32_e32 v10, 16, v141
	v_pk_mul_f32 v[10:11], v[38:39], v[10:11]
	s_andn2_b64 vcc, exec, s[38:39]
	v_add_f32_e32 v10, 0, v10
	v_add_f32_e32 v14, v10, v11
	v_and_b32_e32 v11, 0xffff0000, v143
	v_and_b32_e32 v10, 0xffff0000, v141
	v_pk_mul_f32 v[10:11], v[34:35], v[10:11]
	s_nop 0
	v_add_f32_e32 v10, 0, v10
	v_add_f32_e32 v15, v10, v11
	v_lshlrev_b32_e32 v11, 16, v138
	v_lshlrev_b32_e32 v10, 16, v136
	v_pk_mul_f32 v[8:9], v[8:9], v[10:11]
	s_nop 0
	v_add_f32_e32 v8, v12, v8
	v_add_f32_e32 v10, v8, v9
	v_and_b32_e32 v9, 0xffff0000, v138
	v_and_b32_e32 v8, 0xffff0000, v136
	v_pk_mul_f32 v[6:7], v[6:7], v[8:9]
	s_nop 0
	v_add_f32_e32 v6, v13, v6
	v_add_f32_e32 v8, v6, v7
	v_lshlrev_b32_e32 v7, 16, v139
	v_lshlrev_b32_e32 v6, 16, v137
	v_pk_mul_f32 v[4:5], v[4:5], v[6:7]
	s_nop 0
	v_add_f32_e32 v4, v14, v4
	v_add_f32_e32 v6, v4, v5
	v_and_b32_e32 v5, 0xffff0000, v139
	v_and_b32_e32 v4, 0xffff0000, v137
	v_pk_mul_f32 v[0:1], v[0:1], v[4:5]
	s_nop 0
	v_add_f32_e32 v0, v15, v0
	v_add_f32_e32 v1, v0, v1
	v_cvt_pk_bf16_f32 v0, v10, v8
	v_cvt_pk_bf16_f32 v1, v6, v1
	global_store_dwordx2 v[2:3], v[0:1], off
	s_cbranch_vccnz .LBB0_713
	s_andn2_b64 vcc, exec, s[0:1]
	s_cbranch_vccnz .LBB0_712
	s_branch .LBB0_712

.LBB0_787:
	s_add_u32 s28, s50, 0xfff80080
	s_addc_u32 s29, s51, -1
	s_add_i32 s94, 0, 0x10000
	s_cmp_eq_u32 s93, 28
	s_cselect_b32 s53, s43, s29
	s_cselect_b32 s52, s91, s28
	s_cselect_b32 s29, s41, s92
	s_cselect_b32 s28, vcc_lo, vcc_hi
	s_add_i32 s96, 0, 0x14000
	s_waitcnt vmcnt(0)
	v_add_u32_e32 v142, s94, v207
	v_add_u32_e32 v158, s96, v207
	ds_read_b128 v[130:133], v142
	ds_read_b128 v[134:137], v142 offset:1024
	ds_read_b128 v[138:141], v142 offset:2048
	ds_read_b128 v[142:145], v142 offset:3072
	ds_read_b128 v[146:149], v158
	ds_read_b128 v[150:153], v158 offset:1024
	ds_read_b128 v[154:157], v158 offset:2048
	ds_read_b128 v[158:161], v158 offset:3072
	v_lshl_add_u64 v[204:205], s[50:51], 0, v[192:193]
	s_add_i32 m0, s59, 0xc000
	ds_read_b128 v[162:165], v224
	ds_read_b128 v[166:169], v224 offset:1024
	ds_read_b128 v[170:173], v224 offset:2048
	ds_read_b128 v[174:177], v224 offset:3072
	ds_read_b128 v[178:181], v224 offset:4096
	ds_read_b128 v[182:185], v224 offset:5120
	ds_read_b128 v[196:199], v224 offset:6144
	ds_read_b128 v[200:203], v224 offset:7168
	global_load_lds_dwordx4 v[204:205], off
	v_lshl_add_u64 v[204:205], s[50:51], 0, v[194:195]
	s_add_i32 m0, s59, 0xe000
	s_nop 0
	global_load_lds_dwordx4 v[204:205], off
	s_waitcnt vmcnt(8)
	s_waitcnt lgkmcnt(0)
	s_barrier
	s_setprio 1
	s_waitcnt lgkmcnt(0)
	v_mfma_f32_16x16x32_bf16 v[126:129], v[130:133], v[162:165], v[126:129]
	v_mfma_f32_16x16x32_bf16 v[122:125], v[138:141], v[162:165], v[122:125]
	v_mfma_f32_16x16x32_bf16 v[114:117], v[130:133], v[170:173], v[114:117]
	v_mfma_f32_16x16x32_bf16 v[106:109], v[138:141], v[170:173], v[106:109]
	v_mfma_f32_16x16x32_bf16 v[98:101], v[130:133], v[178:181], v[98:101]
	v_mfma_f32_16x16x32_bf16 v[90:93], v[138:141], v[178:181], v[90:93]
	v_mfma_f32_16x16x32_bf16 v[82:85], v[130:133], v[196:199], v[82:85]
	v_mfma_f32_16x16x32_bf16 v[74:77], v[138:141], v[196:199], v[74:77]
	v_mfma_f32_16x16x32_bf16 v[126:129], v[134:137], v[166:169], v[126:129]
	v_mfma_f32_16x16x32_bf16 v[122:125], v[142:145], v[166:169], v[122:125]
	v_mfma_f32_16x16x32_bf16 v[114:117], v[134:137], v[174:177], v[114:117]
	v_mfma_f32_16x16x32_bf16 v[106:109], v[142:145], v[174:177], v[106:109]
	v_mfma_f32_16x16x32_bf16 v[98:101], v[134:137], v[182:185], v[98:101]
	v_mfma_f32_16x16x32_bf16 v[90:93], v[142:145], v[182:185], v[90:93]
	v_mfma_f32_16x16x32_bf16 v[82:85], v[134:137], v[200:203], v[82:85]
	v_mfma_f32_16x16x32_bf16 v[74:77], v[142:145], v[200:203], v[74:77]
	s_setprio 0
	s_setprio 1
	v_mfma_f32_16x16x32_bf16 v[118:121], v[146:149], v[162:165], v[118:121]
	v_mfma_f32_16x16x32_bf16 v[110:113], v[154:157], v[162:165], v[110:113]
	v_mfma_f32_16x16x32_bf16 v[102:105], v[146:149], v[170:173], v[102:105]
	v_mfma_f32_16x16x32_bf16 v[94:97], v[154:157], v[170:173], v[94:97]
	v_mfma_f32_16x16x32_bf16 v[86:89], v[146:149], v[178:181], v[86:89]
	v_mfma_f32_16x16x32_bf16 v[78:81], v[154:157], v[178:181], v[78:81]
	v_mfma_f32_16x16x32_bf16 v[70:73], v[146:149], v[196:199], v[70:73]
	v_mfma_f32_16x16x32_bf16 v[66:69], v[154:157], v[196:199], v[66:69]
	v_mfma_f32_16x16x32_bf16 v[118:121], v[150:153], v[166:169], v[118:121]
	v_mfma_f32_16x16x32_bf16 v[110:113], v[158:161], v[166:169], v[110:113]
	v_mfma_f32_16x16x32_bf16 v[102:105], v[150:153], v[174:177], v[102:105]
	v_mfma_f32_16x16x32_bf16 v[94:97], v[158:161], v[174:177], v[94:97]
	v_mfma_f32_16x16x32_bf16 v[86:89], v[150:153], v[182:185], v[86:89]
	v_mfma_f32_16x16x32_bf16 v[78:81], v[158:161], v[182:185], v[78:81]
	v_mfma_f32_16x16x32_bf16 v[70:73], v[150:153], v[200:203], v[70:73]
	v_mfma_f32_16x16x32_bf16 v[66:69], v[158:161], v[200:203], v[66:69]
	s_setprio 0
	s_barrier
	s_add_i32 s94, s94, s37
	v_lshl_add_u64 v[204:205], s[28:29], 0, v[16:17]
	s_mov_b32 m0, s94
	ds_read_b128 v[162:165], v224 offset:16384
	ds_read_b128 v[166:169], v224 offset:17408
	ds_read_b128 v[170:173], v224 offset:18432
	ds_read_b128 v[174:177], v224 offset:19456
	ds_read_b128 v[178:181], v224 offset:20480
	ds_read_b128 v[182:185], v224 offset:21504
	ds_read_b128 v[196:199], v224 offset:22528
	ds_read_b128 v[200:203], v224 offset:23552
	global_load_lds_dwordx4 v[204:205], off
	s_add_i32 m0, s94, 0x2000
	s_add_u32 s94, s28, 0x80000
	v_lshl_add_u64 v[226:227], s[28:29], 0, v[186:187]
	s_addc_u32 s95, s29, 0
	s_add_i32 s96, s96, s37
	global_load_lds_dwordx4 v[226:227], off
	v_lshl_add_u64 v[228:229], s[94:95], 0, v[16:17]
	s_mov_b32 m0, s96
	v_lshl_add_u64 v[230:231], s[52:53], 0, v[188:189]
	global_load_lds_dwordx4 v[228:229], off
	v_lshl_add_u64 v[228:229], s[94:95], 0, v[186:187]
	s_add_i32 m0, s96, 0x2000
	s_nop 0
	global_load_lds_dwordx4 v[228:229], off
	v_lshl_add_u64 v[228:229], s[52:53], 0, v[190:191]
	s_mov_b32 m0, s59
	s_nop 0
	global_load_lds_dwordx4 v[228:229], off
	s_mov_b32 m0, s83
	s_nop 0
	global_load_lds_dwordx4 v[230:231], off
	s_waitcnt vmcnt(8)
	s_waitcnt lgkmcnt(0)
	s_barrier
	s_setprio 1
	s_waitcnt lgkmcnt(0)
	v_mfma_f32_16x16x32_bf16 v[62:65], v[130:133], v[162:165], v[62:65]
	v_mfma_f32_16x16x32_bf16 v[58:61], v[138:141], v[162:165], v[58:61]
	v_mfma_f32_16x16x32_bf16 v[50:53], v[130:133], v[170:173], v[50:53]
	v_mfma_f32_16x16x32_bf16 v[42:45], v[138:141], v[170:173], v[42:45]
	v_mfma_f32_16x16x32_bf16 v[34:37], v[130:133], v[178:181], v[34:37]
	v_mfma_f32_16x16x32_bf16 v[26:29], v[138:141], v[178:181], v[26:29]
	v_mfma_f32_16x16x32_bf16 v[18:21], v[130:133], v[196:199], v[18:21]
	v_mfma_f32_16x16x32_bf16 v[8:11], v[138:141], v[196:199], v[8:11]
	v_mfma_f32_16x16x32_bf16 v[62:65], v[134:137], v[166:169], v[62:65]
	v_mfma_f32_16x16x32_bf16 v[58:61], v[142:145], v[166:169], v[58:61]
	v_mfma_f32_16x16x32_bf16 v[50:53], v[134:137], v[174:177], v[50:53]
	v_mfma_f32_16x16x32_bf16 v[42:45], v[142:145], v[174:177], v[42:45]
	v_mfma_f32_16x16x32_bf16 v[34:37], v[134:137], v[182:185], v[34:37]
	v_mfma_f32_16x16x32_bf16 v[26:29], v[142:145], v[182:185], v[26:29]
	v_mfma_f32_16x16x32_bf16 v[18:21], v[134:137], v[200:203], v[18:21]
	v_mfma_f32_16x16x32_bf16 v[8:11], v[142:145], v[200:203], v[8:11]
	s_setprio 0
	s_setprio 1
	v_mfma_f32_16x16x32_bf16 v[54:57], v[146:149], v[162:165], v[54:57]
	v_mfma_f32_16x16x32_bf16 v[46:49], v[154:157], v[162:165], v[46:49]
	v_mfma_f32_16x16x32_bf16 v[38:41], v[146:149], v[170:173], v[38:41]
	v_mfma_f32_16x16x32_bf16 v[30:33], v[154:157], v[170:173], v[30:33]
	v_mfma_f32_16x16x32_bf16 v[22:25], v[146:149], v[178:181], v[22:25]
	v_mfma_f32_16x16x32_bf16 v[12:15], v[154:157], v[178:181], v[12:15]
	v_mfma_f32_16x16x32_bf16 v[4:7], v[146:149], v[196:199], v[4:7]
	v_mfma_f32_16x16x32_bf16 v[0:3], v[154:157], v[196:199], v[0:3]
	v_mfma_f32_16x16x32_bf16 v[54:57], v[150:153], v[166:169], v[54:57]
	v_mfma_f32_16x16x32_bf16 v[46:49], v[158:161], v[166:169], v[46:49]
	v_mfma_f32_16x16x32_bf16 v[38:41], v[150:153], v[174:177], v[38:41]
	v_mfma_f32_16x16x32_bf16 v[30:33], v[158:161], v[174:177], v[30:33]
	v_mfma_f32_16x16x32_bf16 v[22:25], v[150:153], v[182:185], v[22:25]
	v_mfma_f32_16x16x32_bf16 v[12:15], v[158:161], v[182:185], v[12:15]
	v_mfma_f32_16x16x32_bf16 v[4:7], v[150:153], v[200:203], v[4:7]
	v_mfma_f32_16x16x32_bf16 v[0:3], v[158:161], v[200:203], v[0:3]
	s_setprio 0
	s_barrier
	s_add_i32 s94, 0, 0x18000
	s_add_i32 s95, 0, 0x1c000
	v_add_u32_e32 v142, s94, v207
	v_add_u32_e32 v158, s95, v207
	ds_read_b128 v[130:133], v142
	ds_read_b128 v[134:137], v142 offset:1024
	ds_read_b128 v[138:141], v142 offset:2048
	ds_read_b128 v[142:145], v142 offset:3072
	ds_read_b128 v[146:149], v158
	ds_read_b128 v[150:153], v158 offset:1024
	ds_read_b128 v[154:157], v158 offset:2048
	ds_read_b128 v[158:161], v158 offset:3072
	s_add_u32 s52, s52, 0x80000
	s_addc_u32 s53, s53, 0
	s_mov_b32 m0, s84
	v_lshl_add_u64 v[232:233], s[52:53], 0, v[190:191]
	ds_read_b128 v[162:165], v224 offset:32768
	ds_read_b128 v[166:169], v224 offset:33792
	ds_read_b128 v[170:173], v224 offset:34816
	ds_read_b128 v[174:177], v224 offset:35840
	ds_read_b128 v[178:181], v224 offset:36864
	ds_read_b128 v[182:185], v224 offset:37888
	ds_read_b128 v[196:199], v224 offset:38912
	ds_read_b128 v[200:203], v224 offset:39936
	global_load_lds_dwordx4 v[232:233], off
	v_lshl_add_u64 v[232:233], s[52:53], 0, v[188:189]
	s_mov_b32 m0, s85
	s_nop 0
	global_load_lds_dwordx4 v[232:233], off
	s_waitcnt vmcnt(8)
	s_waitcnt lgkmcnt(0)
	s_barrier
	s_setprio 1
	s_waitcnt lgkmcnt(0)
	v_mfma_f32_16x16x32_bf16 v[126:129], v[130:133], v[162:165], v[126:129]
	v_mfma_f32_16x16x32_bf16 v[122:125], v[138:141], v[162:165], v[122:125]
	v_mfma_f32_16x16x32_bf16 v[114:117], v[130:133], v[170:173], v[114:117]
	v_mfma_f32_16x16x32_bf16 v[106:109], v[138:141], v[170:173], v[106:109]
	v_mfma_f32_16x16x32_bf16 v[98:101], v[130:133], v[178:181], v[98:101]
	v_mfma_f32_16x16x32_bf16 v[90:93], v[138:141], v[178:181], v[90:93]
	v_mfma_f32_16x16x32_bf16 v[82:85], v[130:133], v[196:199], v[82:85]
	v_mfma_f32_16x16x32_bf16 v[74:77], v[138:141], v[196:199], v[74:77]
	v_mfma_f32_16x16x32_bf16 v[126:129], v[134:137], v[166:169], v[126:129]
	v_mfma_f32_16x16x32_bf16 v[122:125], v[142:145], v[166:169], v[122:125]
	v_mfma_f32_16x16x32_bf16 v[114:117], v[134:137], v[174:177], v[114:117]
	v_mfma_f32_16x16x32_bf16 v[106:109], v[142:145], v[174:177], v[106:109]
	v_mfma_f32_16x16x32_bf16 v[98:101], v[134:137], v[182:185], v[98:101]
	v_mfma_f32_16x16x32_bf16 v[90:93], v[142:145], v[182:185], v[90:93]
	v_mfma_f32_16x16x32_bf16 v[82:85], v[134:137], v[200:203], v[82:85]
	v_mfma_f32_16x16x32_bf16 v[74:77], v[142:145], v[200:203], v[74:77]
	s_setprio 0
	s_setprio 1
	v_mfma_f32_16x16x32_bf16 v[118:121], v[146:149], v[162:165], v[118:121]
	v_mfma_f32_16x16x32_bf16 v[110:113], v[154:157], v[162:165], v[110:113]
	v_mfma_f32_16x16x32_bf16 v[102:105], v[146:149], v[170:173], v[102:105]
	v_mfma_f32_16x16x32_bf16 v[94:97], v[154:157], v[170:173], v[94:97]
	v_mfma_f32_16x16x32_bf16 v[86:89], v[146:149], v[178:181], v[86:89]
	v_mfma_f32_16x16x32_bf16 v[78:81], v[154:157], v[178:181], v[78:81]
	v_mfma_f32_16x16x32_bf16 v[70:73], v[146:149], v[196:199], v[70:73]
	v_mfma_f32_16x16x32_bf16 v[66:69], v[154:157], v[196:199], v[66:69]
	v_mfma_f32_16x16x32_bf16 v[118:121], v[150:153], v[166:169], v[118:121]
	v_mfma_f32_16x16x32_bf16 v[110:113], v[158:161], v[166:169], v[110:113]
	v_mfma_f32_16x16x32_bf16 v[102:105], v[150:153], v[174:177], v[102:105]
	v_mfma_f32_16x16x32_bf16 v[94:97], v[158:161], v[174:177], v[94:97]
	v_mfma_f32_16x16x32_bf16 v[86:89], v[150:153], v[182:185], v[86:89]
	v_mfma_f32_16x16x32_bf16 v[78:81], v[158:161], v[182:185], v[78:81]
	v_mfma_f32_16x16x32_bf16 v[70:73], v[150:153], v[200:203], v[70:73]
	v_mfma_f32_16x16x32_bf16 v[66:69], v[158:161], v[200:203], v[66:69]
	s_setprio 0
	s_barrier
	s_add_i32 s52, s94, s37
	v_lshl_add_u64 v[204:205], v[204:205], 0, s[34:35]
	s_mov_b32 m0, s52
	ds_read_b128 v[162:165], v224 offset:49152
	ds_read_b128 v[166:169], v224 offset:50176
	ds_read_b128 v[170:173], v224 offset:51200
	ds_read_b128 v[174:177], v224 offset:52224
	ds_read_b128 v[178:181], v224 offset:53248
	ds_read_b128 v[182:185], v224 offset:54272
	ds_read_b128 v[196:199], v224 offset:55296
	ds_read_b128 v[200:203], v224 offset:56320
	global_load_lds_dwordx4 v[204:205], off
	s_add_i32 m0, s52, 0x2000
	s_add_u32 s28, s28, 0x80080
	v_lshl_add_u64 v[204:205], v[226:227], 0, s[34:35]
	s_addc_u32 s29, s29, 0
	s_add_i32 s52, s95, s37
	global_load_lds_dwordx4 v[204:205], off
	v_lshl_add_u64 v[204:205], s[28:29], 0, v[16:17]
	s_mov_b32 m0, s52
	s_nop 0
	global_load_lds_dwordx4 v[204:205], off
	v_lshl_add_u64 v[204:205], s[28:29], 0, v[186:187]
	s_add_i32 m0, s52, 0x2000
	s_nop 0
	global_load_lds_dwordx4 v[204:205], off
	v_lshl_add_u64 v[204:205], v[228:229], 0, s[34:35]
	s_mov_b32 m0, s88
	s_nop 0
	global_load_lds_dwordx4 v[204:205], off
	v_lshl_add_u64 v[204:205], v[230:231], 0, s[34:35]
	s_mov_b32 m0, s89
	s_nop 0
	global_load_lds_dwordx4 v[204:205], off
	s_waitcnt vmcnt(8)
	s_waitcnt lgkmcnt(0)
	s_barrier
	s_setprio 1
	s_waitcnt lgkmcnt(0)
	v_mfma_f32_16x16x32_bf16 v[62:65], v[130:133], v[162:165], v[62:65]
	v_mfma_f32_16x16x32_bf16 v[58:61], v[138:141], v[162:165], v[58:61]
	v_mfma_f32_16x16x32_bf16 v[50:53], v[130:133], v[170:173], v[50:53]
	v_mfma_f32_16x16x32_bf16 v[42:45], v[138:141], v[170:173], v[42:45]
	v_mfma_f32_16x16x32_bf16 v[34:37], v[130:133], v[178:181], v[34:37]
	v_mfma_f32_16x16x32_bf16 v[26:29], v[138:141], v[178:181], v[26:29]
	v_mfma_f32_16x16x32_bf16 v[18:21], v[130:133], v[196:199], v[18:21]
	v_mfma_f32_16x16x32_bf16 v[8:11], v[138:141], v[196:199], v[8:11]
	v_mfma_f32_16x16x32_bf16 v[62:65], v[134:137], v[166:169], v[62:65]
	v_mfma_f32_16x16x32_bf16 v[58:61], v[142:145], v[166:169], v[58:61]
	v_mfma_f32_16x16x32_bf16 v[50:53], v[134:137], v[174:177], v[50:53]
	v_mfma_f32_16x16x32_bf16 v[42:45], v[142:145], v[174:177], v[42:45]
	v_mfma_f32_16x16x32_bf16 v[34:37], v[134:137], v[182:185], v[34:37]
	v_mfma_f32_16x16x32_bf16 v[26:29], v[142:145], v[182:185], v[26:29]
	v_mfma_f32_16x16x32_bf16 v[18:21], v[134:137], v[200:203], v[18:21]
	v_mfma_f32_16x16x32_bf16 v[8:11], v[142:145], v[200:203], v[8:11]
	s_setprio 0
	s_setprio 1
	v_mfma_f32_16x16x32_bf16 v[54:57], v[146:149], v[162:165], v[54:57]
	v_mfma_f32_16x16x32_bf16 v[46:49], v[154:157], v[162:165], v[46:49]
	v_mfma_f32_16x16x32_bf16 v[38:41], v[146:149], v[170:173], v[38:41]
	v_mfma_f32_16x16x32_bf16 v[30:33], v[154:157], v[170:173], v[30:33]
	v_mfma_f32_16x16x32_bf16 v[22:25], v[146:149], v[178:181], v[22:25]
	v_mfma_f32_16x16x32_bf16 v[12:15], v[154:157], v[178:181], v[12:15]
	v_mfma_f32_16x16x32_bf16 v[4:7], v[146:149], v[196:199], v[4:7]
	v_mfma_f32_16x16x32_bf16 v[0:3], v[154:157], v[196:199], v[0:3]
	v_mfma_f32_16x16x32_bf16 v[54:57], v[150:153], v[166:169], v[54:57]
	v_mfma_f32_16x16x32_bf16 v[46:49], v[158:161], v[166:169], v[46:49]
	v_mfma_f32_16x16x32_bf16 v[38:41], v[150:153], v[174:177], v[38:41]
	v_mfma_f32_16x16x32_bf16 v[30:33], v[158:161], v[174:177], v[30:33]
	v_mfma_f32_16x16x32_bf16 v[22:25], v[150:153], v[182:185], v[22:25]
	v_mfma_f32_16x16x32_bf16 v[12:15], v[158:161], v[182:185], v[12:15]
	v_mfma_f32_16x16x32_bf16 v[4:7], v[150:153], v[200:203], v[4:7]
	v_mfma_f32_16x16x32_bf16 v[0:3], v[158:161], v[200:203], v[0:3]
	s_setprio 0
	s_barrier
	s_add_i32 s93, s93, 2
	s_add_u32 s50, s50, 0x100
	s_addc_u32 s51, s51, 0
	s_add_u32 vcc_hi, vcc_hi, 0x100
	s_addc_u32 s92, s92, 0
	s_cmp_gt_u32 s93, 29
	s_cbranch_scc0 .LBB0_787
	s_and_b64 vcc, exec, s[22:23]
	s_cbranch_vccz .LBB0_790
.LBB0_790:
	s_cmp_gt_i32 s48, 63
	s_cselect_b64 s[28:29], -1, 0
	s_mov_b64 s[50:51], 0x18000
	s_and_b64 vcc, exec, s[28:29]
	s_mov_b64 s[92:93], 0x2000
	s_cbranch_vccnz .LBB0_792
	s_ashr_i32 s41, s48, 3
	s_mul_hi_i32 s51, s41, 0x3000
	s_mul_i32 s50, s41, 0x3000

.LBB0_799:
	s_andn2_b64 vcc, exec, s[38:39]
	s_mov_b64 s[28:29], -1
	s_mov_b64 s[8:9], s[10:11]
	s_cbranch_vccnz .LBB0_783
	s_andn2_b64 vcc, exec, s[18:19]
	s_cbranch_vccnz .LBB0_782
	s_branch .LBB0_782

.LBB0_803:
	s_and_b64 vcc, exec, s[22:23]
	s_cbranch_vccz .Lsg_G_nb
	s_barrier

.LBB0_923:
	v_mul_f32_e32 v145, 0xbfb8aa3b, v126
	v_exp_f32_e32 v145, v145
	v_lshl_or_b32 v146, s85, 7, v142
	v_lshl_add_u32 v144, s44, 8, v140
	v_ashrrev_i32_e32 v147, 31, v146
	v_add_f32_e32 v145, 1.0, v145
	v_rcp_f32_e32 v145, v145
	s_andn2_b64 vcc, exec, s[38:39]
	s_mov_b64 s[92:93], 0x2000
	s_mov_b64 s[90:91], s[62:63]
	v_mul_f32_e32 v126, v126, v145
	v_mul_f32_e32 v122, v126, v122
	v_mul_f32_e32 v126, 0xbfb8aa3b, v127
	v_exp_f32_e32 v126, v126
	s_nop 0
	v_add_f32_e32 v126, 1.0, v126
	v_rcp_f32_e32 v126, v126
	s_nop 0
	v_mul_f32_e32 v126, v127, v126
	v_mul_f32_e32 v123, v126, v123
	v_mul_f32_e32 v126, 0xbfb8aa3b, v128
	v_exp_f32_e32 v126, v126
	s_nop 0
	v_add_f32_e32 v126, 1.0, v126
	v_rcp_f32_e32 v126, v126
	s_nop 0
	v_mul_f32_e32 v126, v128, v126
	v_mul_f32_e32 v124, v126, v124
	v_mul_f32_e32 v126, 0xbfb8aa3b, v129
	v_exp_f32_e32 v126, v126
	s_nop 0
	v_add_f32_e32 v126, 1.0, v126
	v_rcp_f32_e32 v126, v126
	s_nop 0
	v_mul_f32_e32 v126, v129, v126
	v_mul_f32_e32 v125, v126, v125
	v_mul_f32_e32 v126, 0xbfb8aa3b, v118
	v_exp_f32_e32 v126, v126
	s_nop 0
	v_add_f32_e32 v126, 1.0, v126
	v_rcp_f32_e32 v126, v126
	s_nop 0
	v_mul_f32_e32 v118, v118, v126
	v_mul_f32_e32 v114, v118, v114
	v_mul_f32_e32 v118, 0xbfb8aa3b, v119
	v_exp_f32_e32 v118, v118
	s_nop 0
	v_add_f32_e32 v118, 1.0, v118
	v_rcp_f32_e32 v118, v118
	s_nop 0
	v_mul_f32_e32 v118, v119, v118
	v_mul_f32_e32 v115, v118, v115
	v_mul_f32_e32 v118, 0xbfb8aa3b, v120
	v_exp_f32_e32 v118, v118
	s_nop 0
	v_add_f32_e32 v118, 1.0, v118
	v_rcp_f32_e32 v118, v118
	s_nop 0
	v_mul_f32_e32 v118, v120, v118
	v_mul_f32_e32 v116, v118, v116
	v_mul_f32_e32 v118, 0xbfb8aa3b, v121
	v_exp_f32_e32 v118, v118
	s_nop 0
	v_add_f32_e32 v118, 1.0, v118
	v_rcp_f32_e32 v118, v118
	s_nop 0
	v_mul_f32_e32 v118, v121, v118
	v_mul_f32_e32 v117, v118, v117
	v_cvt_pk_bf16_f32 v118, v122, v123
	v_cvt_pk_bf16_f32 v119, v124, v125
	v_cvt_pk_bf16_f32 v120, v114, v115
	v_mov_b64_e32 v[114:115], s[70:71]
	v_cvt_pk_bf16_f32 v121, v116, v117
	v_mad_i64_i32 v[122:123], s[28:29], v144, s76, v[114:115]
	v_lshlrev_b64 v[116:117], 1, v[146:147]
	v_lshl_add_u64 v[122:123], v[122:123], 0, v[116:117]
	global_store_dwordx4 v[122:123], v[118:121], off
	s_nop 1
	v_mul_f32_e32 v118, 0xbfb8aa3b, v110
	v_exp_f32_e32 v118, v118
	s_nop 0
	v_add_f32_e32 v118, 1.0, v118
	v_rcp_f32_e32 v118, v118
	s_nop 0
	v_mul_f32_e32 v110, v110, v118
	v_mul_f32_e32 v106, v110, v106
	v_mul_f32_e32 v110, 0xbfb8aa3b, v111
	v_exp_f32_e32 v110, v110
	s_nop 0
	v_add_f32_e32 v110, 1.0, v110
	v_rcp_f32_e32 v110, v110
	s_nop 0
	v_mul_f32_e32 v110, v111, v110
	v_mul_f32_e32 v107, v110, v107
	v_mul_f32_e32 v110, 0xbfb8aa3b, v112
	v_exp_f32_e32 v110, v110
	s_nop 0
	v_add_f32_e32 v110, 1.0, v110
	v_rcp_f32_e32 v110, v110
	s_nop 0
	v_mul_f32_e32 v110, v112, v110
	v_mul_f32_e32 v108, v110, v108
	v_mul_f32_e32 v110, 0xbfb8aa3b, v113
	v_exp_f32_e32 v110, v110
	s_nop 0
	v_add_f32_e32 v110, 1.0, v110
	v_rcp_f32_e32 v110, v110
	s_nop 0
	v_mul_f32_e32 v110, v113, v110
	v_mul_f32_e32 v109, v110, v109
	v_mul_f32_e32 v110, 0xbfb8aa3b, v102
	v_exp_f32_e32 v110, v110
	s_nop 0
	v_add_f32_e32 v110, 1.0, v110
	v_rcp_f32_e32 v110, v110
	s_nop 0
	v_mul_f32_e32 v102, v102, v110
	v_mul_f32_e32 v102, v102, v98
	v_mul_f32_e32 v98, 0xbfb8aa3b, v103
	v_exp_f32_e32 v98, v98
	s_nop 0
	v_add_f32_e32 v98, 1.0, v98
	v_rcp_f32_e32 v98, v98
	s_nop 0
	v_mul_f32_e32 v98, v103, v98
	v_mul_f32_e32 v103, v98, v99
	v_mul_f32_e32 v98, 0xbfb8aa3b, v104
	v_exp_f32_e32 v98, v98
	s_nop 0
	v_add_f32_e32 v98, 1.0, v98
	v_rcp_f32_e32 v98, v98
	s_nop 0
	v_mul_f32_e32 v98, v104, v98
	v_mul_f32_e32 v104, v98, v100
	v_mul_f32_e32 v98, 0xbfb8aa3b, v105
	v_exp_f32_e32 v98, v98
	s_nop 0
	v_add_f32_e32 v98, 1.0, v98
	v_rcp_f32_e32 v98, v98
	s_nop 0
	v_mul_f32_e32 v98, v105, v98
	v_mul_f32_e32 v101, v98, v101
	v_cvt_pk_bf16_f32 v98, v106, v107
	v_cvt_pk_bf16_f32 v99, v108, v109
	v_cvt_pk_bf16_f32 v100, v102, v103
	v_or_b32_e32 v102, 16, v144
	v_mad_i64_i32 v[102:103], s[28:29], v102, s76, v[114:115]
	v_lshl_add_u64 v[102:103], v[102:103], 0, v[116:117]
	v_cvt_pk_bf16_f32 v101, v104, v101
	global_store_dwordx4 v[102:103], v[98:101], off
	s_nop 1
	v_mul_f32_e32 v98, 0xbfb8aa3b, v94
	v_exp_f32_e32 v98, v98
	s_nop 0
	v_add_f32_e32 v98, 1.0, v98
	v_rcp_f32_e32 v98, v98
	s_nop 0
	v_mul_f32_e32 v94, v94, v98
	v_mul_f32_e32 v90, v94, v90
	v_mul_f32_e32 v94, 0xbfb8aa3b, v95
	v_exp_f32_e32 v94, v94
	s_nop 0
	v_add_f32_e32 v94, 1.0, v94
	v_rcp_f32_e32 v94, v94
	s_nop 0
	v_mul_f32_e32 v94, v95, v94
	v_mul_f32_e32 v91, v94, v91
	v_mul_f32_e32 v94, 0xbfb8aa3b, v96
	v_exp_f32_e32 v94, v94
	s_nop 0
	v_add_f32_e32 v94, 1.0, v94
	v_rcp_f32_e32 v94, v94
	s_nop 0
	v_mul_f32_e32 v94, v96, v94
	v_mul_f32_e32 v92, v94, v92
	v_mul_f32_e32 v94, 0xbfb8aa3b, v97
	v_exp_f32_e32 v94, v94
	s_nop 0
	v_add_f32_e32 v94, 1.0, v94
	v_rcp_f32_e32 v94, v94
	s_nop 0
	v_mul_f32_e32 v94, v97, v94
	v_mul_f32_e32 v93, v94, v93
	v_mul_f32_e32 v94, 0xbfb8aa3b, v86
	v_exp_f32_e32 v94, v94
	s_nop 0
	v_add_f32_e32 v94, 1.0, v94
	v_rcp_f32_e32 v94, v94
	s_nop 0
	v_mul_f32_e32 v86, v86, v94
	v_mul_f32_e32 v86, v86, v82
	v_mul_f32_e32 v82, 0xbfb8aa3b, v87
	v_exp_f32_e32 v82, v82
	s_nop 0
	v_add_f32_e32 v82, 1.0, v82
	v_rcp_f32_e32 v82, v82
	s_nop 0
	v_mul_f32_e32 v82, v87, v82
	v_mul_f32_e32 v87, v82, v83
	v_mul_f32_e32 v82, 0xbfb8aa3b, v88
	v_exp_f32_e32 v82, v82
	s_nop 0
	v_add_f32_e32 v82, 1.0, v82
	v_rcp_f32_e32 v82, v82
	s_nop 0
	v_mul_f32_e32 v82, v88, v82
	v_mul_f32_e32 v88, v82, v84
	v_mul_f32_e32 v82, 0xbfb8aa3b, v89
	v_exp_f32_e32 v82, v82
	s_nop 0
	v_add_f32_e32 v82, 1.0, v82
	v_rcp_f32_e32 v82, v82
	s_nop 0
	v_mul_f32_e32 v82, v89, v82
	v_mul_f32_e32 v85, v82, v85
	v_cvt_pk_bf16_f32 v82, v90, v91
	v_cvt_pk_bf16_f32 v83, v92, v93
	v_cvt_pk_bf16_f32 v84, v86, v87
	v_or_b32_e32 v86, 32, v144
	v_mad_i64_i32 v[86:87], s[28:29], v86, s76, v[114:115]
	v_lshl_add_u64 v[86:87], v[86:87], 0, v[116:117]
	v_cvt_pk_bf16_f32 v85, v88, v85
	global_store_dwordx4 v[86:87], v[82:85], off
	s_nop 1
	v_mul_f32_e32 v82, 0xbfb8aa3b, v78
	v_exp_f32_e32 v82, v82
	s_nop 0
	v_add_f32_e32 v82, 1.0, v82
	v_rcp_f32_e32 v82, v82
	s_nop 0
	v_mul_f32_e32 v78, v78, v82
	v_mul_f32_e32 v74, v78, v74
	v_mul_f32_e32 v78, 0xbfb8aa3b, v79
	v_exp_f32_e32 v78, v78
	s_nop 0
	v_add_f32_e32 v78, 1.0, v78
	v_rcp_f32_e32 v78, v78
	s_nop 0
	v_mul_f32_e32 v78, v79, v78
	v_mul_f32_e32 v75, v78, v75
	v_mul_f32_e32 v78, 0xbfb8aa3b, v80
	v_exp_f32_e32 v78, v78
	s_nop 0
	v_add_f32_e32 v78, 1.0, v78
	v_rcp_f32_e32 v78, v78
	s_nop 0
	v_mul_f32_e32 v78, v80, v78
	v_mul_f32_e32 v76, v78, v76
	v_mul_f32_e32 v78, 0xbfb8aa3b, v81
	v_exp_f32_e32 v78, v78
	s_nop 0
	v_add_f32_e32 v78, 1.0, v78
	v_rcp_f32_e32 v78, v78
	s_nop 0
	v_mul_f32_e32 v78, v81, v78
	v_mul_f32_e32 v77, v78, v77
	v_mul_f32_e32 v78, 0xbfb8aa3b, v70
	v_exp_f32_e32 v78, v78
	s_nop 0
	v_add_f32_e32 v78, 1.0, v78
	v_rcp_f32_e32 v78, v78
	s_nop 0
	v_mul_f32_e32 v70, v70, v78
	v_mul_f32_e32 v70, v70, v66
	v_mul_f32_e32 v66, 0xbfb8aa3b, v71
	v_exp_f32_e32 v66, v66
	s_nop 0
	v_add_f32_e32 v66, 1.0, v66
	v_rcp_f32_e32 v66, v66
	s_nop 0
	v_mul_f32_e32 v66, v71, v66
	v_mul_f32_e32 v71, v66, v67
	v_mul_f32_e32 v66, 0xbfb8aa3b, v72
	v_exp_f32_e32 v66, v66
	s_nop 0
	v_add_f32_e32 v66, 1.0, v66
	v_rcp_f32_e32 v66, v66
	s_nop 0
	v_mul_f32_e32 v66, v72, v66
	v_mul_f32_e32 v72, v66, v68
	v_mul_f32_e32 v66, 0xbfb8aa3b, v73
	v_exp_f32_e32 v66, v66
	s_nop 0
	v_add_f32_e32 v66, 1.0, v66
	v_rcp_f32_e32 v66, v66
	s_nop 0
	v_mul_f32_e32 v66, v73, v66
	v_mul_f32_e32 v69, v66, v69
	v_cvt_pk_bf16_f32 v66, v74, v75
	v_cvt_pk_bf16_f32 v67, v76, v77
	v_cvt_pk_bf16_f32 v68, v70, v71
	v_or_b32_e32 v70, 48, v144
	v_mad_i64_i32 v[70:71], s[28:29], v70, s76, v[114:115]
	v_lshl_add_u64 v[70:71], v[70:71], 0, v[116:117]
	v_cvt_pk_bf16_f32 v69, v72, v69
	global_store_dwordx4 v[70:71], v[66:69], off
	s_nop 1
	v_mul_f32_e32 v67, 0xbfb8aa3b, v62
	v_exp_f32_e32 v67, v67
	v_add_u32_e32 v66, 0x80, v144
	v_add_f32_e32 v67, 1.0, v67
	v_rcp_f32_e32 v67, v67
	s_nop 0
	v_mul_f32_e32 v62, v62, v67
	v_mul_f32_e32 v58, v62, v58
	v_mul_f32_e32 v62, 0xbfb8aa3b, v63
	v_exp_f32_e32 v62, v62
	s_nop 0
	v_add_f32_e32 v62, 1.0, v62
	v_rcp_f32_e32 v62, v62
	s_nop 0
	v_mul_f32_e32 v62, v63, v62
	v_mul_f32_e32 v59, v62, v59
	v_mul_f32_e32 v62, 0xbfb8aa3b, v64
	v_exp_f32_e32 v62, v62
	s_nop 0
	v_add_f32_e32 v62, 1.0, v62
	v_rcp_f32_e32 v62, v62
	s_nop 0
	v_mul_f32_e32 v62, v64, v62
	v_mul_f32_e32 v60, v62, v60
	v_mul_f32_e32 v62, 0xbfb8aa3b, v65
	v_exp_f32_e32 v62, v62
	s_nop 0
	v_add_f32_e32 v62, 1.0, v62
	v_rcp_f32_e32 v62, v62
	s_nop 0
	v_mul_f32_e32 v62, v65, v62
	v_mul_f32_e32 v61, v62, v61
	v_mul_f32_e32 v62, 0xbfb8aa3b, v54
	v_exp_f32_e32 v62, v62
	s_nop 0
	v_add_f32_e32 v62, 1.0, v62
	v_rcp_f32_e32 v62, v62
	s_nop 0
	v_mul_f32_e32 v54, v54, v62
	v_mul_f32_e32 v54, v54, v50
	v_mul_f32_e32 v50, 0xbfb8aa3b, v55
	v_exp_f32_e32 v50, v50
	s_nop 0
	v_add_f32_e32 v50, 1.0, v50
	v_rcp_f32_e32 v50, v50
	s_nop 0
	v_mul_f32_e32 v50, v55, v50
	v_mul_f32_e32 v55, v50, v51
	v_mul_f32_e32 v50, 0xbfb8aa3b, v56
	v_exp_f32_e32 v50, v50
	s_nop 0
	v_add_f32_e32 v50, 1.0, v50
	v_rcp_f32_e32 v50, v50
	s_nop 0
	v_mul_f32_e32 v50, v56, v50
	v_mul_f32_e32 v56, v50, v52
	v_mul_f32_e32 v50, 0xbfb8aa3b, v57
	v_exp_f32_e32 v50, v50
	s_nop 0
	v_add_f32_e32 v50, 1.0, v50
	v_rcp_f32_e32 v50, v50
	s_nop 0
	v_mul_f32_e32 v50, v57, v50
	v_mul_f32_e32 v53, v50, v53
	v_cvt_pk_bf16_f32 v50, v58, v59
	v_cvt_pk_bf16_f32 v51, v60, v61
	v_cvt_pk_bf16_f32 v52, v54, v55
	v_mad_i64_i32 v[54:55], s[28:29], v66, s76, v[114:115]
	v_lshl_add_u64 v[54:55], v[54:55], 0, v[116:117]
	v_cvt_pk_bf16_f32 v53, v56, v53
	global_store_dwordx4 v[54:55], v[50:53], off
	s_nop 1
	v_mul_f32_e32 v50, 0xbfb8aa3b, v46
	v_exp_f32_e32 v50, v50
	s_nop 0
	v_add_f32_e32 v50, 1.0, v50
	v_rcp_f32_e32 v50, v50
	s_nop 0
	v_mul_f32_e32 v46, v46, v50
	v_mul_f32_e32 v42, v46, v42
	v_mul_f32_e32 v46, 0xbfb8aa3b, v47
	v_exp_f32_e32 v46, v46
	s_nop 0
	v_add_f32_e32 v46, 1.0, v46
	v_rcp_f32_e32 v46, v46
	s_nop 0
	v_mul_f32_e32 v46, v47, v46
	v_mul_f32_e32 v43, v46, v43
	v_mul_f32_e32 v46, 0xbfb8aa3b, v48
	v_exp_f32_e32 v46, v46
	s_nop 0
	v_add_f32_e32 v46, 1.0, v46
	v_rcp_f32_e32 v46, v46
	s_nop 0
	v_mul_f32_e32 v46, v48, v46
	v_mul_f32_e32 v44, v46, v44
	v_mul_f32_e32 v46, 0xbfb8aa3b, v49
	v_exp_f32_e32 v46, v46
	s_nop 0
	v_add_f32_e32 v46, 1.0, v46
	v_rcp_f32_e32 v46, v46
	s_nop 0
	v_mul_f32_e32 v46, v49, v46
	v_mul_f32_e32 v45, v46, v45
	v_mul_f32_e32 v46, 0xbfb8aa3b, v38
	v_exp_f32_e32 v46, v46
	s_nop 0
	v_add_f32_e32 v46, 1.0, v46
	v_rcp_f32_e32 v46, v46
	s_nop 0
	v_mul_f32_e32 v38, v38, v46
	v_mul_f32_e32 v38, v38, v34
	v_mul_f32_e32 v34, 0xbfb8aa3b, v39
	v_exp_f32_e32 v34, v34
	s_nop 0
	v_add_f32_e32 v34, 1.0, v34
	v_rcp_f32_e32 v34, v34
	s_nop 0
	v_mul_f32_e32 v34, v39, v34
	v_mul_f32_e32 v39, v34, v35
	v_mul_f32_e32 v34, 0xbfb8aa3b, v40
	v_exp_f32_e32 v34, v34
	s_nop 0
	v_add_f32_e32 v34, 1.0, v34
	v_rcp_f32_e32 v34, v34
	s_nop 0
	v_mul_f32_e32 v34, v40, v34
	v_mul_f32_e32 v40, v34, v36
	v_mul_f32_e32 v34, 0xbfb8aa3b, v41
	v_exp_f32_e32 v34, v34
	s_nop 0
	v_add_f32_e32 v34, 1.0, v34
	v_rcp_f32_e32 v34, v34
	s_nop 0
	v_mul_f32_e32 v34, v41, v34
	v_mul_f32_e32 v37, v34, v37
	v_cvt_pk_bf16_f32 v34, v42, v43
	v_cvt_pk_bf16_f32 v35, v44, v45
	v_cvt_pk_bf16_f32 v36, v38, v39
	v_add_u32_e32 v38, 0x90, v144
	v_mad_i64_i32 v[38:39], s[28:29], v38, s76, v[114:115]
	v_lshl_add_u64 v[38:39], v[38:39], 0, v[116:117]
	v_cvt_pk_bf16_f32 v37, v40, v37
	global_store_dwordx4 v[38:39], v[34:37], off
	s_nop 1
	v_mul_f32_e32 v34, 0xbfb8aa3b, v30
	v_exp_f32_e32 v34, v34
	s_nop 0
	v_add_f32_e32 v34, 1.0, v34
	v_rcp_f32_e32 v34, v34
	s_nop 0
	v_mul_f32_e32 v30, v30, v34
	v_mul_f32_e32 v26, v30, v26
	v_mul_f32_e32 v30, 0xbfb8aa3b, v31
	v_exp_f32_e32 v30, v30
	s_nop 0
	v_add_f32_e32 v30, 1.0, v30
	v_rcp_f32_e32 v30, v30
	s_nop 0
	v_mul_f32_e32 v30, v31, v30
	v_mul_f32_e32 v27, v30, v27
	v_mul_f32_e32 v30, 0xbfb8aa3b, v32
	v_exp_f32_e32 v30, v30
	s_nop 0
	v_add_f32_e32 v30, 1.0, v30
	v_rcp_f32_e32 v30, v30
	s_nop 0
	v_mul_f32_e32 v30, v32, v30
	v_mul_f32_e32 v28, v30, v28
	v_mul_f32_e32 v30, 0xbfb8aa3b, v33
	v_exp_f32_e32 v30, v30
	s_nop 0
	v_add_f32_e32 v30, 1.0, v30
	v_rcp_f32_e32 v30, v30
	s_nop 0
	v_mul_f32_e32 v30, v33, v30
	v_mul_f32_e32 v29, v30, v29
	v_mul_f32_e32 v30, 0xbfb8aa3b, v22
	v_exp_f32_e32 v30, v30
	s_nop 0
	v_add_f32_e32 v30, 1.0, v30
	v_rcp_f32_e32 v30, v30
	s_nop 0
	v_mul_f32_e32 v22, v22, v30
	v_mul_f32_e32 v22, v22, v18
	v_mul_f32_e32 v18, 0xbfb8aa3b, v23
	v_exp_f32_e32 v18, v18
	s_nop 0
	v_add_f32_e32 v18, 1.0, v18
	v_rcp_f32_e32 v18, v18
	s_nop 0
	v_mul_f32_e32 v18, v23, v18
	v_mul_f32_e32 v23, v18, v19
	v_mul_f32_e32 v18, 0xbfb8aa3b, v24
	v_exp_f32_e32 v18, v18
	s_nop 0
	v_add_f32_e32 v18, 1.0, v18
	v_rcp_f32_e32 v18, v18
	s_nop 0
	v_mul_f32_e32 v18, v24, v18
	v_mul_f32_e32 v24, v18, v20
	v_mul_f32_e32 v18, 0xbfb8aa3b, v25
	v_exp_f32_e32 v18, v18
	s_nop 0
	v_add_f32_e32 v18, 1.0, v18
	v_rcp_f32_e32 v18, v18
	s_nop 0
	v_mul_f32_e32 v18, v25, v18
	v_mul_f32_e32 v21, v18, v21
	v_cvt_pk_bf16_f32 v18, v26, v27
	v_cvt_pk_bf16_f32 v19, v28, v29
	v_cvt_pk_bf16_f32 v20, v22, v23
	v_add_u32_e32 v22, 0xa0, v144
	v_mad_i64_i32 v[22:23], s[28:29], v22, s76, v[114:115]
	v_lshl_add_u64 v[22:23], v[22:23], 0, v[116:117]
	v_cvt_pk_bf16_f32 v21, v24, v21
	global_store_dwordx4 v[22:23], v[18:21], off
	s_nop 1
	v_mul_f32_e32 v18, 0xbfb8aa3b, v12
	v_exp_f32_e32 v18, v18
	s_nop 0
	v_add_f32_e32 v18, 1.0, v18
	v_rcp_f32_e32 v18, v18
	s_nop 0
	v_mul_f32_e32 v12, v12, v18
	v_mul_f32_e32 v8, v12, v8
	v_mul_f32_e32 v12, 0xbfb8aa3b, v13
	v_exp_f32_e32 v12, v12
	s_nop 0
	v_add_f32_e32 v12, 1.0, v12
	v_rcp_f32_e32 v12, v12
	s_nop 0
	v_mul_f32_e32 v12, v13, v12
	v_mul_f32_e32 v9, v12, v9
	v_mul_f32_e32 v12, 0xbfb8aa3b, v14
	v_exp_f32_e32 v12, v12
	s_nop 0
	v_add_f32_e32 v12, 1.0, v12
	v_rcp_f32_e32 v12, v12
	s_nop 0
	v_mul_f32_e32 v12, v14, v12
	v_mul_f32_e32 v10, v12, v10
	v_mul_f32_e32 v12, 0xbfb8aa3b, v15
	v_exp_f32_e32 v12, v12
	s_nop 0
	v_add_f32_e32 v12, 1.0, v12
	v_rcp_f32_e32 v12, v12
	s_nop 0
	v_mul_f32_e32 v12, v15, v12
	v_mul_f32_e32 v11, v12, v11
	v_mul_f32_e32 v12, 0xbfb8aa3b, v4
	v_exp_f32_e32 v12, v12
	s_nop 0
	v_add_f32_e32 v12, 1.0, v12
	v_rcp_f32_e32 v12, v12
	s_nop 0
	v_mul_f32_e32 v4, v4, v12
	v_mul_f32_e32 v4, v4, v0
	v_mul_f32_e32 v0, 0xbfb8aa3b, v5
	v_exp_f32_e32 v0, v0
	s_nop 0
	v_add_f32_e32 v0, 1.0, v0
	v_rcp_f32_e32 v0, v0
	s_nop 0
	v_mul_f32_e32 v0, v5, v0
	v_mul_f32_e32 v5, v0, v1
	v_mul_f32_e32 v0, 0xbfb8aa3b, v6
	v_exp_f32_e32 v0, v0
	s_nop 0
	v_add_f32_e32 v0, 1.0, v0
	v_rcp_f32_e32 v0, v0
	s_nop 0
	v_mul_f32_e32 v0, v6, v0
	v_mul_f32_e32 v6, v0, v2
	v_mul_f32_e32 v0, 0xbfb8aa3b, v7
	v_exp_f32_e32 v0, v0
	s_nop 0
	v_add_f32_e32 v0, 1.0, v0
	v_rcp_f32_e32 v0, v0
	s_nop 0
	v_mul_f32_e32 v0, v7, v0
	v_mul_f32_e32 v3, v0, v3
	v_cvt_pk_bf16_f32 v0, v8, v9
	v_cvt_pk_bf16_f32 v1, v10, v11
	v_cvt_pk_bf16_f32 v2, v4, v5
	v_add_u32_e32 v4, 0xb0, v144
	v_mad_i64_i32 v[4:5], s[28:29], v4, s76, v[114:115]
	v_lshl_add_u64 v[4:5], v[4:5], 0, v[116:117]
	s_mov_b64 s[28:29], -1
	v_cvt_pk_bf16_f32 v3, v6, v3
	global_store_dwordx4 v[4:5], v[0:3], off
	s_cbranch_vccnz .LBB0_916
	s_andn2_b64 vcc, exec, s[14:15]
	s_cbranch_vccnz .LBB0_915
	s_branch .LBB0_915

.LBB0_992:
	s_add_u32 s36, s26, 0x100
	s_addc_u32 s37, s27, 0
	s_add_i32 s87, 0, 0x10000
	s_cmpk_eq_i32 s86, 0x54
	s_cselect_b32 s41, s19, s37
	s_cselect_b32 s40, s18, s36
	s_cselect_b32 s29, s23, s43
	s_cselect_b32 s28, s22, s42
	s_add_i32 s88, 0, 0x14000
	v_add_u32_e32 v142, s87, v203
	v_add_u32_e32 v158, s88, v203
	ds_read_b128 v[130:133], v142
	ds_read_b128 v[134:137], v142 offset:1024
	ds_read_b128 v[138:141], v142 offset:2048
	ds_read_b128 v[142:145], v142 offset:3072
	ds_read_b128 v[146:149], v158
	ds_read_b128 v[150:153], v158 offset:1024
	ds_read_b128 v[154:157], v158 offset:2048
	ds_read_b128 v[158:161], v158 offset:3072
	v_lshl_add_u64 v[200:201], s[26:27], 0, v[188:189]
	s_add_i32 m0, s47, 0xc000
	ds_read_b128 v[162:165], v205
	ds_read_b128 v[166:169], v205 offset:1024
	ds_read_b128 v[170:173], v205 offset:2048
	ds_read_b128 v[174:177], v205 offset:3072
	ds_read_b128 v[178:181], v205 offset:4096
	ds_read_b128 v[192:195], v205 offset:5120
	ds_read_b128 v[196:199], v205 offset:6144
	ds_read_b128 v[224:227], v205 offset:7168
	global_load_lds_dwordx4 v[200:201], off
	v_lshl_add_u64 v[200:201], s[26:27], 0, v[190:191]
	s_add_i32 m0, s47, 0xe000
	s_nop 0
	global_load_lds_dwordx4 v[200:201], off
	s_waitcnt vmcnt(8)
	s_waitcnt lgkmcnt(0)
	s_barrier
	s_setprio 1
	s_waitcnt lgkmcnt(0)
	v_mfma_f32_16x16x32_bf16 v[126:129], v[130:133], v[162:165], v[126:129]
	v_mfma_f32_16x16x32_bf16 v[122:125], v[138:141], v[162:165], v[122:125]
	v_mfma_f32_16x16x32_bf16 v[114:117], v[130:133], v[170:173], v[114:117]
	v_mfma_f32_16x16x32_bf16 v[106:109], v[138:141], v[170:173], v[106:109]
	v_mfma_f32_16x16x32_bf16 v[98:101], v[130:133], v[178:181], v[98:101]
	v_mfma_f32_16x16x32_bf16 v[90:93], v[138:141], v[178:181], v[90:93]
	v_mfma_f32_16x16x32_bf16 v[82:85], v[130:133], v[196:199], v[82:85]
	v_mfma_f32_16x16x32_bf16 v[74:77], v[138:141], v[196:199], v[74:77]
	v_mfma_f32_16x16x32_bf16 v[126:129], v[134:137], v[166:169], v[126:129]
	v_mfma_f32_16x16x32_bf16 v[122:125], v[142:145], v[166:169], v[122:125]
	v_mfma_f32_16x16x32_bf16 v[114:117], v[134:137], v[174:177], v[114:117]
	v_mfma_f32_16x16x32_bf16 v[106:109], v[142:145], v[174:177], v[106:109]
	v_mfma_f32_16x16x32_bf16 v[98:101], v[134:137], v[192:195], v[98:101]
	v_mfma_f32_16x16x32_bf16 v[90:93], v[142:145], v[192:195], v[90:93]
	v_mfma_f32_16x16x32_bf16 v[82:85], v[134:137], v[224:227], v[82:85]
	v_mfma_f32_16x16x32_bf16 v[74:77], v[142:145], v[224:227], v[74:77]
	s_setprio 0
	s_setprio 1
	v_mfma_f32_16x16x32_bf16 v[118:121], v[146:149], v[162:165], v[118:121]
	v_mfma_f32_16x16x32_bf16 v[110:113], v[154:157], v[162:165], v[110:113]
	v_mfma_f32_16x16x32_bf16 v[102:105], v[146:149], v[170:173], v[102:105]
	v_mfma_f32_16x16x32_bf16 v[94:97], v[154:157], v[170:173], v[94:97]
	v_mfma_f32_16x16x32_bf16 v[86:89], v[146:149], v[178:181], v[86:89]
	v_mfma_f32_16x16x32_bf16 v[78:81], v[154:157], v[178:181], v[78:81]
	v_mfma_f32_16x16x32_bf16 v[70:73], v[146:149], v[196:199], v[70:73]
	v_mfma_f32_16x16x32_bf16 v[66:69], v[154:157], v[196:199], v[66:69]
	v_mfma_f32_16x16x32_bf16 v[118:121], v[150:153], v[166:169], v[118:121]
	v_mfma_f32_16x16x32_bf16 v[110:113], v[158:161], v[166:169], v[110:113]
	v_mfma_f32_16x16x32_bf16 v[102:105], v[150:153], v[174:177], v[102:105]
	v_mfma_f32_16x16x32_bf16 v[94:97], v[158:161], v[174:177], v[94:97]
	v_mfma_f32_16x16x32_bf16 v[86:89], v[150:153], v[192:195], v[86:89]
	v_mfma_f32_16x16x32_bf16 v[78:81], v[158:161], v[192:195], v[78:81]
	v_mfma_f32_16x16x32_bf16 v[70:73], v[150:153], v[224:227], v[70:73]
	v_mfma_f32_16x16x32_bf16 v[66:69], v[158:161], v[224:227], v[66:69]
	s_setprio 0
	s_barrier
	s_add_i32 s26, s87, s45
	v_lshl_add_u64 v[200:201], s[28:29], 0, v[16:17]
	s_mov_b32 m0, s26
	ds_read_b128 v[162:165], v205 offset:16384
	ds_read_b128 v[166:169], v205 offset:17408
	ds_read_b128 v[170:173], v205 offset:18432
	ds_read_b128 v[174:177], v205 offset:19456
	ds_read_b128 v[178:181], v205 offset:20480
	ds_read_b128 v[192:195], v205 offset:21504
	ds_read_b128 v[196:199], v205 offset:22528
	ds_read_b128 v[224:227], v205 offset:23552
	global_load_lds_dwordx4 v[200:201], off
	s_add_i32 m0, s26, 0x2000
	s_add_u32 s26, s28, 0x160000
	v_lshl_add_u64 v[206:207], s[28:29], 0, v[182:183]
	s_addc_u32 s27, s29, 0
	s_add_i32 s87, s88, s45
	global_load_lds_dwordx4 v[206:207], off
	v_lshl_add_u64 v[216:217], s[26:27], 0, v[16:17]
	s_mov_b32 m0, s87
	v_lshl_add_u64 v[228:229], s[40:41], 0, v[184:185]
	global_load_lds_dwordx4 v[216:217], off
	v_lshl_add_u64 v[216:217], s[26:27], 0, v[182:183]
	s_add_i32 m0, s87, 0x2000
	s_nop 0
	global_load_lds_dwordx4 v[216:217], off
	v_lshl_add_u64 v[216:217], s[40:41], 0, v[186:187]
	s_mov_b32 m0, s47
	s_nop 0
	global_load_lds_dwordx4 v[216:217], off
	s_mov_b32 m0, s48
	s_nop 0
	global_load_lds_dwordx4 v[228:229], off
	s_waitcnt vmcnt(8)
	s_waitcnt lgkmcnt(0)
	s_barrier
	s_setprio 1
	s_waitcnt lgkmcnt(0)
	v_mfma_f32_16x16x32_bf16 v[62:65], v[130:133], v[162:165], v[62:65]
	v_mfma_f32_16x16x32_bf16 v[58:61], v[138:141], v[162:165], v[58:61]
	v_mfma_f32_16x16x32_bf16 v[50:53], v[130:133], v[170:173], v[50:53]
	v_mfma_f32_16x16x32_bf16 v[42:45], v[138:141], v[170:173], v[42:45]
	v_mfma_f32_16x16x32_bf16 v[34:37], v[130:133], v[178:181], v[34:37]
	v_mfma_f32_16x16x32_bf16 v[26:29], v[138:141], v[178:181], v[26:29]
	v_mfma_f32_16x16x32_bf16 v[18:21], v[130:133], v[196:199], v[18:21]
	v_mfma_f32_16x16x32_bf16 v[8:11], v[138:141], v[196:199], v[8:11]
	v_mfma_f32_16x16x32_bf16 v[62:65], v[134:137], v[166:169], v[62:65]
	v_mfma_f32_16x16x32_bf16 v[58:61], v[142:145], v[166:169], v[58:61]
	v_mfma_f32_16x16x32_bf16 v[50:53], v[134:137], v[174:177], v[50:53]
	v_mfma_f32_16x16x32_bf16 v[42:45], v[142:145], v[174:177], v[42:45]
	v_mfma_f32_16x16x32_bf16 v[34:37], v[134:137], v[192:195], v[34:37]
	v_mfma_f32_16x16x32_bf16 v[26:29], v[142:145], v[192:195], v[26:29]
	v_mfma_f32_16x16x32_bf16 v[18:21], v[134:137], v[224:227], v[18:21]
	v_mfma_f32_16x16x32_bf16 v[8:11], v[142:145], v[224:227], v[8:11]
	s_setprio 0
	s_setprio 1
	v_mfma_f32_16x16x32_bf16 v[54:57], v[146:149], v[162:165], v[54:57]
	v_mfma_f32_16x16x32_bf16 v[46:49], v[154:157], v[162:165], v[46:49]
	v_mfma_f32_16x16x32_bf16 v[38:41], v[146:149], v[170:173], v[38:41]
	v_mfma_f32_16x16x32_bf16 v[30:33], v[154:157], v[170:173], v[30:33]
	v_mfma_f32_16x16x32_bf16 v[22:25], v[146:149], v[178:181], v[22:25]
	v_mfma_f32_16x16x32_bf16 v[12:15], v[154:157], v[178:181], v[12:15]
	v_mfma_f32_16x16x32_bf16 v[4:7], v[146:149], v[196:199], v[4:7]
	v_mfma_f32_16x16x32_bf16 v[0:3], v[154:157], v[196:199], v[0:3]
	v_mfma_f32_16x16x32_bf16 v[54:57], v[150:153], v[166:169], v[54:57]
	v_mfma_f32_16x16x32_bf16 v[46:49], v[158:161], v[166:169], v[46:49]
	v_mfma_f32_16x16x32_bf16 v[38:41], v[150:153], v[174:177], v[38:41]
	v_mfma_f32_16x16x32_bf16 v[30:33], v[158:161], v[174:177], v[30:33]
	v_mfma_f32_16x16x32_bf16 v[22:25], v[150:153], v[192:195], v[22:25]
	v_mfma_f32_16x16x32_bf16 v[12:15], v[158:161], v[192:195], v[12:15]
	v_mfma_f32_16x16x32_bf16 v[4:7], v[150:153], v[224:227], v[4:7]
	v_mfma_f32_16x16x32_bf16 v[0:3], v[158:161], v[224:227], v[0:3]
	s_setprio 0
	s_barrier
	s_add_i32 s87, 0, 0x18000
	s_add_i32 s88, 0, 0x1c000
	v_add_u32_e32 v142, s87, v203
	v_add_u32_e32 v158, s88, v203
	ds_read_b128 v[130:133], v142
	ds_read_b128 v[134:137], v142 offset:1024
	ds_read_b128 v[138:141], v142 offset:2048
	ds_read_b128 v[142:145], v142 offset:3072
	ds_read_b128 v[146:149], v158
	ds_read_b128 v[150:153], v158 offset:1024
	ds_read_b128 v[154:157], v158 offset:2048
	ds_read_b128 v[158:161], v158 offset:3072
	s_add_u32 s26, s40, 0x160000
	s_addc_u32 s27, s41, 0
	s_mov_b32 m0, s49
	v_lshl_add_u64 v[230:231], s[26:27], 0, v[186:187]
	ds_read_b128 v[162:165], v205 offset:32768
	ds_read_b128 v[166:169], v205 offset:33792
	ds_read_b128 v[170:173], v205 offset:34816
	ds_read_b128 v[174:177], v205 offset:35840
	ds_read_b128 v[178:181], v205 offset:36864
	ds_read_b128 v[192:195], v205 offset:37888
	ds_read_b128 v[196:199], v205 offset:38912
	ds_read_b128 v[224:227], v205 offset:39936
	global_load_lds_dwordx4 v[230:231], off
	v_lshl_add_u64 v[230:231], s[26:27], 0, v[184:185]
	s_mov_b32 m0, s50
	s_nop 0
	global_load_lds_dwordx4 v[230:231], off
	s_waitcnt vmcnt(8)
	s_waitcnt lgkmcnt(0)
	s_barrier
	s_setprio 1
	s_waitcnt lgkmcnt(0)
	v_mfma_f32_16x16x32_bf16 v[126:129], v[130:133], v[162:165], v[126:129]
	v_mfma_f32_16x16x32_bf16 v[122:125], v[138:141], v[162:165], v[122:125]
	v_mfma_f32_16x16x32_bf16 v[114:117], v[130:133], v[170:173], v[114:117]
	v_mfma_f32_16x16x32_bf16 v[106:109], v[138:141], v[170:173], v[106:109]
	v_mfma_f32_16x16x32_bf16 v[98:101], v[130:133], v[178:181], v[98:101]
	v_mfma_f32_16x16x32_bf16 v[90:93], v[138:141], v[178:181], v[90:93]
	v_mfma_f32_16x16x32_bf16 v[82:85], v[130:133], v[196:199], v[82:85]
	v_mfma_f32_16x16x32_bf16 v[74:77], v[138:141], v[196:199], v[74:77]
	v_mfma_f32_16x16x32_bf16 v[126:129], v[134:137], v[166:169], v[126:129]
	v_mfma_f32_16x16x32_bf16 v[122:125], v[142:145], v[166:169], v[122:125]
	v_mfma_f32_16x16x32_bf16 v[114:117], v[134:137], v[174:177], v[114:117]
	v_mfma_f32_16x16x32_bf16 v[106:109], v[142:145], v[174:177], v[106:109]
	v_mfma_f32_16x16x32_bf16 v[98:101], v[134:137], v[192:195], v[98:101]
	v_mfma_f32_16x16x32_bf16 v[90:93], v[142:145], v[192:195], v[90:93]
	v_mfma_f32_16x16x32_bf16 v[82:85], v[134:137], v[224:227], v[82:85]
	v_mfma_f32_16x16x32_bf16 v[74:77], v[142:145], v[224:227], v[74:77]
	s_setprio 0
	s_setprio 1
	v_mfma_f32_16x16x32_bf16 v[118:121], v[146:149], v[162:165], v[118:121]
	v_mfma_f32_16x16x32_bf16 v[110:113], v[154:157], v[162:165], v[110:113]
	v_mfma_f32_16x16x32_bf16 v[102:105], v[146:149], v[170:173], v[102:105]
	v_mfma_f32_16x16x32_bf16 v[94:97], v[154:157], v[170:173], v[94:97]
	v_mfma_f32_16x16x32_bf16 v[86:89], v[146:149], v[178:181], v[86:89]
	v_mfma_f32_16x16x32_bf16 v[78:81], v[154:157], v[178:181], v[78:81]
	v_mfma_f32_16x16x32_bf16 v[70:73], v[146:149], v[196:199], v[70:73]
	v_mfma_f32_16x16x32_bf16 v[66:69], v[154:157], v[196:199], v[66:69]
	v_mfma_f32_16x16x32_bf16 v[118:121], v[150:153], v[166:169], v[118:121]
	v_mfma_f32_16x16x32_bf16 v[110:113], v[158:161], v[166:169], v[110:113]
	v_mfma_f32_16x16x32_bf16 v[102:105], v[150:153], v[174:177], v[102:105]
	v_mfma_f32_16x16x32_bf16 v[94:97], v[158:161], v[174:177], v[94:97]
	v_mfma_f32_16x16x32_bf16 v[86:89], v[150:153], v[192:195], v[86:89]
	v_mfma_f32_16x16x32_bf16 v[78:81], v[158:161], v[192:195], v[78:81]
	v_mfma_f32_16x16x32_bf16 v[70:73], v[150:153], v[224:227], v[70:73]
	v_mfma_f32_16x16x32_bf16 v[66:69], v[158:161], v[224:227], v[66:69]
	s_setprio 0
	s_barrier
	s_add_i32 s26, s87, s45
	v_lshl_add_u64 v[200:201], v[200:201], 0, s[34:35]
	s_mov_b32 m0, s26
	ds_read_b128 v[162:165], v205 offset:49152
	ds_read_b128 v[166:169], v205 offset:50176
	ds_read_b128 v[170:173], v205 offset:51200
	ds_read_b128 v[174:177], v205 offset:52224
	ds_read_b128 v[178:181], v205 offset:53248
	ds_read_b128 v[192:195], v205 offset:54272
	ds_read_b128 v[196:199], v205 offset:55296
	ds_read_b128 v[224:227], v205 offset:56320
	global_load_lds_dwordx4 v[200:201], off
	s_add_i32 m0, s26, 0x2000
	s_add_u32 s26, s28, 0x160080
	v_lshl_add_u64 v[200:201], v[206:207], 0, s[34:35]
	s_addc_u32 s27, s29, 0
	s_add_i32 s28, s88, s45
	global_load_lds_dwordx4 v[200:201], off
	v_lshl_add_u64 v[200:201], s[26:27], 0, v[16:17]
	s_mov_b32 m0, s28
	s_nop 0
	global_load_lds_dwordx4 v[200:201], off
	v_lshl_add_u64 v[200:201], s[26:27], 0, v[182:183]
	s_add_i32 m0, s28, 0x2000
	s_nop 0
	global_load_lds_dwordx4 v[200:201], off
	v_lshl_add_u64 v[200:201], v[216:217], 0, s[34:35]
	s_mov_b32 m0, s53
	s_nop 0
	global_load_lds_dwordx4 v[200:201], off
	v_lshl_add_u64 v[200:201], v[228:229], 0, s[34:35]
	s_mov_b32 m0, s57
	s_nop 0
	global_load_lds_dwordx4 v[200:201], off
	s_waitcnt vmcnt(8)
	s_waitcnt lgkmcnt(0)
	s_barrier
	s_setprio 1
	s_waitcnt lgkmcnt(0)
	v_mfma_f32_16x16x32_bf16 v[62:65], v[130:133], v[162:165], v[62:65]
	v_mfma_f32_16x16x32_bf16 v[58:61], v[138:141], v[162:165], v[58:61]
	v_mfma_f32_16x16x32_bf16 v[50:53], v[130:133], v[170:173], v[50:53]
	v_mfma_f32_16x16x32_bf16 v[42:45], v[138:141], v[170:173], v[42:45]
	v_mfma_f32_16x16x32_bf16 v[34:37], v[130:133], v[178:181], v[34:37]
	v_mfma_f32_16x16x32_bf16 v[26:29], v[138:141], v[178:181], v[26:29]
	v_mfma_f32_16x16x32_bf16 v[18:21], v[130:133], v[196:199], v[18:21]
	v_mfma_f32_16x16x32_bf16 v[8:11], v[138:141], v[196:199], v[8:11]
	v_mfma_f32_16x16x32_bf16 v[62:65], v[134:137], v[166:169], v[62:65]
	v_mfma_f32_16x16x32_bf16 v[58:61], v[142:145], v[166:169], v[58:61]
	v_mfma_f32_16x16x32_bf16 v[50:53], v[134:137], v[174:177], v[50:53]
	v_mfma_f32_16x16x32_bf16 v[42:45], v[142:145], v[174:177], v[42:45]
	v_mfma_f32_16x16x32_bf16 v[34:37], v[134:137], v[192:195], v[34:37]
	v_mfma_f32_16x16x32_bf16 v[26:29], v[142:145], v[192:195], v[26:29]
	v_mfma_f32_16x16x32_bf16 v[18:21], v[134:137], v[224:227], v[18:21]
	v_mfma_f32_16x16x32_bf16 v[8:11], v[142:145], v[224:227], v[8:11]
	s_setprio 0
	s_setprio 1
	v_mfma_f32_16x16x32_bf16 v[54:57], v[146:149], v[162:165], v[54:57]
	v_mfma_f32_16x16x32_bf16 v[46:49], v[154:157], v[162:165], v[46:49]
	v_mfma_f32_16x16x32_bf16 v[38:41], v[146:149], v[170:173], v[38:41]
	v_mfma_f32_16x16x32_bf16 v[30:33], v[154:157], v[170:173], v[30:33]
	v_mfma_f32_16x16x32_bf16 v[22:25], v[146:149], v[178:181], v[22:25]
	v_mfma_f32_16x16x32_bf16 v[12:15], v[154:157], v[178:181], v[12:15]
	v_mfma_f32_16x16x32_bf16 v[4:7], v[146:149], v[196:199], v[4:7]
	v_mfma_f32_16x16x32_bf16 v[0:3], v[154:157], v[196:199], v[0:3]
	v_mfma_f32_16x16x32_bf16 v[54:57], v[150:153], v[166:169], v[54:57]
	v_mfma_f32_16x16x32_bf16 v[46:49], v[158:161], v[166:169], v[46:49]
	v_mfma_f32_16x16x32_bf16 v[38:41], v[150:153], v[174:177], v[38:41]
	v_mfma_f32_16x16x32_bf16 v[30:33], v[158:161], v[174:177], v[30:33]
	v_mfma_f32_16x16x32_bf16 v[22:25], v[150:153], v[192:195], v[22:25]
	v_mfma_f32_16x16x32_bf16 v[12:15], v[158:161], v[192:195], v[12:15]
	v_mfma_f32_16x16x32_bf16 v[4:7], v[150:153], v[224:227], v[4:7]
	v_mfma_f32_16x16x32_bf16 v[0:3], v[158:161], v[224:227], v[0:3]
	s_setprio 0
	s_barrier
	s_add_i32 s86, s86, 2
	s_add_u32 s42, s42, 0x100
	s_addc_u32 s43, s43, 0
	s_cmpk_gt_u32 s86, 0x55
	s_mov_b64 s[26:27], s[36:37]
	s_cbranch_scc0 .LBB0_992
	s_and_b64 vcc, exec, s[14:15]
	s_cbranch_vccz .LBB0_995
.LBB0_995:
	s_cmp_gt_i32 s84, 63
	s_mov_b64 s[26:27], 0x18000
	s_cbranch_scc1 .LBB0_997
	s_ashr_i32 s26, s84, 3
	s_mul_hi_i32 s27, s26, 0x3000
	s_mulk_i32 s26, 0x3000
.LBB0_997:
	v_lshl_add_u32 v148, s84, 8, v202
	v_ashrrev_i32_e32 v149, 31, v148
	v_lshl_or_b32 v146, s85, 8, v204
	v_lshlrev_b64 v[148:149], 12, v[148:149]
	v_ashrrev_i32_e32 v147, 31, v146
	v_lshl_add_u64 v[148:149], s[4:5], 0, v[148:149]
	v_lshl_add_u64 v[206:207], v[146:147], 1, v[148:149]
	v_add_co_u32_e32 v216, vcc, s67, v206
	s_lshl_b64 s[26:27], s[26:27], 2
	s_nop 0
	v_addc_co_u32_e32 v217, vcc, 0, v207, vcc
	v_add_co_u32_e32 v252, vcc, s17, v206
	s_add_u32 s26, s51, s26
	s_nop 0
	v_addc_co_u32_e32 v253, vcc, 0, v207, vcc
	v_add_co_u32_e32 v200, vcc, s74, v206
	s_addc_u32 s27, s52, s27
	s_nop 0
	v_addc_co_u32_e32 v201, vcc, 0, v207, vcc
	v_add_co_u32_e32 v198, vcc, s64, v206
	v_lshl_add_u64 v[134:135], v[146:147], 2, s[26:27]
	s_nop 0
	v_addc_co_u32_e32 v199, vcc, 0, v207, vcc
	v_add_co_u32_e32 v196, vcc, s31, v206
	s_mov_b32 s26, 0xb0000
	s_nop 0
	v_addc_co_u32_e32 v197, vcc, 0, v207, vcc
	v_add_co_u32_e32 v194, vcc, s65, v206
	global_load_dwordx4 v[138:141], v[134:135], off offset:16
	global_load_dwordx4 v[142:145], v[134:135], off
	global_load_dwordx4 v[130:133], v[134:135], off offset:528
	s_nop 0
	global_load_dwordx4 v[134:137], v[134:135], off offset:512
	v_addc_co_u32_e32 v195, vcc, 0, v207, vcc
	v_add_co_u32_e32 v192, vcc, s26, v206
	global_load_dwordx4 v[224:227], v[206:207], off
	global_load_dwordx4 v[228:231], v[206:207], off offset:256
	v_addc_co_u32_e32 v193, vcc, 0, v207, vcc
	global_load_dwordx4 v[232:235], v[216:217], off
	global_load_dwordx4 v[236:239], v[216:217], off offset:256
	global_load_dwordx4 v[240:243], v[252:253], off
	global_load_dwordx4 v[244:247], v[252:253], off offset:256
	global_load_dwordx4 v[248:251], v[200:201], off
	global_load_dwordx4 v[178:181], v[200:201], off offset:256
	global_load_dwordx4 v[174:177], v[198:199], off
	global_load_dwordx4 v[170:173], v[198:199], off offset:256
	global_load_dwordx4 v[166:169], v[196:197], off
	global_load_dwordx4 v[162:165], v[196:197], off offset:256
	global_load_dwordx4 v[158:161], v[194:195], off
	global_load_dwordx4 v[154:157], v[194:195], off offset:256
	global_load_dwordx4 v[150:153], v[192:193], off
	global_load_dwordx4 v[146:149], v[192:193], off offset:256
	s_waitcnt vmcnt(0)
	v_lshlrev_b32_e32 v223, 16, v224
	v_fmac_f32_e32 v223, v126, v142
	v_and_b32_e32 v126, 0xffff0000, v224
	v_fmac_f32_e32 v126, v127, v143
	v_lshlrev_b32_e32 v127, 16, v225
	v_fmac_f32_e32 v127, v128, v144
	v_and_b32_e32 v128, 0xffff0000, v225
	v_fmac_f32_e32 v128, v129, v145
	v_cvt_pk_bf16_f32 v126, v223, v126
	v_cvt_pk_bf16_f32 v127, v127, v128
	v_lshlrev_b32_e32 v128, 16, v226
	v_fmac_f32_e32 v128, v122, v138
	v_and_b32_e32 v122, 0xffff0000, v226
	v_fmac_f32_e32 v122, v123, v139
	v_cvt_pk_bf16_f32 v128, v128, v122
	v_lshlrev_b32_e32 v122, 16, v227
	v_fmac_f32_e32 v122, v124, v140
	v_and_b32_e32 v123, 0xffff0000, v227
	v_fmac_f32_e32 v123, v125, v141
	v_cvt_pk_bf16_f32 v129, v122, v123
	v_lshlrev_b32_e32 v122, 16, v228
	v_fmac_f32_e32 v122, v118, v134
	v_and_b32_e32 v118, 0xffff0000, v228
	v_fmac_f32_e32 v118, v119, v135
	v_lshlrev_b32_e32 v119, 16, v229
	v_fmac_f32_e32 v119, v120, v136
	v_and_b32_e32 v120, 0xffff0000, v229
	v_fmac_f32_e32 v120, v121, v137
	global_store_dwordx4 v[206:207], v[126:129], off
	v_cvt_pk_bf16_f32 v118, v122, v118
	v_cvt_pk_bf16_f32 v119, v119, v120
	v_lshlrev_b32_e32 v120, 16, v230
	v_fmac_f32_e32 v120, v110, v130
	v_and_b32_e32 v110, 0xffff0000, v230
	v_fmac_f32_e32 v110, v111, v131
	v_cvt_pk_bf16_f32 v120, v120, v110
	v_lshlrev_b32_e32 v110, 16, v231
	v_and_b32_e32 v111, 0xffff0000, v231
	v_fmac_f32_e32 v110, v112, v132
	v_fmac_f32_e32 v111, v113, v133
	v_cvt_pk_bf16_f32 v121, v110, v111
	v_lshlrev_b32_e32 v110, 16, v232
	v_and_b32_e32 v111, 0xffff0000, v232
	v_fmac_f32_e32 v110, v114, v142
	v_fmac_f32_e32 v111, v115, v143
	global_store_dwordx4 v[206:207], v[118:121], off offset:256
	v_cvt_pk_bf16_f32 v110, v110, v111
	v_lshlrev_b32_e32 v111, 16, v233
	v_and_b32_e32 v112, 0xffff0000, v233
	v_fmac_f32_e32 v111, v116, v144
	v_fmac_f32_e32 v112, v117, v145
	v_cvt_pk_bf16_f32 v111, v111, v112
	v_lshlrev_b32_e32 v112, 16, v234
	v_fmac_f32_e32 v112, v106, v138
	v_and_b32_e32 v106, 0xffff0000, v234
	v_fmac_f32_e32 v106, v107, v139
	v_cvt_pk_bf16_f32 v112, v112, v106
	v_lshlrev_b32_e32 v106, 16, v235
	v_fmac_f32_e32 v106, v108, v140
	v_and_b32_e32 v107, 0xffff0000, v235
	v_fmac_f32_e32 v107, v109, v141
	v_cvt_pk_bf16_f32 v113, v106, v107
	v_lshlrev_b32_e32 v106, 16, v236
	v_fmac_f32_e32 v106, v102, v134
	v_and_b32_e32 v102, 0xffff0000, v236
	v_fmac_f32_e32 v102, v103, v135
	v_lshlrev_b32_e32 v103, 16, v237
	v_fmac_f32_e32 v103, v104, v136
	v_and_b32_e32 v104, 0xffff0000, v237
	v_fmac_f32_e32 v104, v105, v137
	global_store_dwordx4 v[216:217], v[110:113], off
	v_cvt_pk_bf16_f32 v102, v106, v102
	v_cvt_pk_bf16_f32 v103, v103, v104
	v_lshlrev_b32_e32 v104, 16, v238
	v_fmac_f32_e32 v104, v94, v130
	v_and_b32_e32 v94, 0xffff0000, v238
	v_fmac_f32_e32 v94, v95, v131
	v_cvt_pk_bf16_f32 v104, v104, v94
	v_lshlrev_b32_e32 v94, 16, v239
	v_and_b32_e32 v95, 0xffff0000, v239
	v_fmac_f32_e32 v94, v96, v132
	v_fmac_f32_e32 v95, v97, v133
	v_cvt_pk_bf16_f32 v105, v94, v95
	v_lshlrev_b32_e32 v94, 16, v240
	v_and_b32_e32 v95, 0xffff0000, v240
	v_fmac_f32_e32 v94, v98, v142
	v_fmac_f32_e32 v95, v99, v143
	global_store_dwordx4 v[216:217], v[102:105], off offset:256
	v_cvt_pk_bf16_f32 v94, v94, v95
	v_lshlrev_b32_e32 v95, 16, v241
	v_and_b32_e32 v96, 0xffff0000, v241
	v_fmac_f32_e32 v95, v100, v144
	v_fmac_f32_e32 v96, v101, v145
	v_cvt_pk_bf16_f32 v95, v95, v96
	v_lshlrev_b32_e32 v96, 16, v242
	v_fmac_f32_e32 v96, v90, v138
	v_and_b32_e32 v90, 0xffff0000, v242
	v_fmac_f32_e32 v90, v91, v139
	v_cvt_pk_bf16_f32 v96, v96, v90
	v_lshlrev_b32_e32 v90, 16, v243
	v_fmac_f32_e32 v90, v92, v140
	v_and_b32_e32 v91, 0xffff0000, v243
	v_fmac_f32_e32 v91, v93, v141
	v_cvt_pk_bf16_f32 v97, v90, v91
	v_lshlrev_b32_e32 v90, 16, v244
	v_fmac_f32_e32 v90, v86, v134
	v_and_b32_e32 v86, 0xffff0000, v244
	v_fmac_f32_e32 v86, v87, v135
	v_lshlrev_b32_e32 v87, 16, v245
	v_fmac_f32_e32 v87, v88, v136
	v_and_b32_e32 v88, 0xffff0000, v245
	v_fmac_f32_e32 v88, v89, v137
	global_store_dwordx4 v[252:253], v[94:97], off
	v_cvt_pk_bf16_f32 v86, v90, v86
	v_cvt_pk_bf16_f32 v87, v87, v88
	v_lshlrev_b32_e32 v88, 16, v246
	v_fmac_f32_e32 v88, v78, v130
	v_and_b32_e32 v78, 0xffff0000, v246
	v_fmac_f32_e32 v78, v79, v131
	v_cvt_pk_bf16_f32 v88, v88, v78
	v_lshlrev_b32_e32 v78, 16, v247
	v_and_b32_e32 v79, 0xffff0000, v247
	v_fmac_f32_e32 v78, v80, v132
	v_fmac_f32_e32 v79, v81, v133
	v_cvt_pk_bf16_f32 v89, v78, v79
	v_lshlrev_b32_e32 v78, 16, v248
	v_and_b32_e32 v79, 0xffff0000, v248
	v_fmac_f32_e32 v78, v82, v142
	v_fmac_f32_e32 v79, v83, v143
	global_store_dwordx4 v[252:253], v[86:89], off offset:256
	v_cvt_pk_bf16_f32 v78, v78, v79
	v_lshlrev_b32_e32 v79, 16, v249
	v_and_b32_e32 v80, 0xffff0000, v249
	v_fmac_f32_e32 v79, v84, v144
	v_fmac_f32_e32 v80, v85, v145
	v_cvt_pk_bf16_f32 v79, v79, v80
	v_lshlrev_b32_e32 v80, 16, v250
	v_fmac_f32_e32 v80, v74, v138
	v_and_b32_e32 v74, 0xffff0000, v250
	v_fmac_f32_e32 v74, v75, v139
	v_cvt_pk_bf16_f32 v80, v80, v74
	v_lshlrev_b32_e32 v74, 16, v251
	v_fmac_f32_e32 v74, v76, v140
	v_and_b32_e32 v75, 0xffff0000, v251
	v_fmac_f32_e32 v75, v77, v141
	v_cvt_pk_bf16_f32 v81, v74, v75
	v_lshlrev_b32_e32 v74, 16, v178
	v_fmac_f32_e32 v74, v70, v134
	v_and_b32_e32 v70, 0xffff0000, v178
	v_fmac_f32_e32 v70, v71, v135
	v_lshlrev_b32_e32 v71, 16, v179
	v_fmac_f32_e32 v71, v72, v136
	v_and_b32_e32 v72, 0xffff0000, v179
	v_fmac_f32_e32 v72, v73, v137
	global_store_dwordx4 v[200:201], v[78:81], off
	v_cvt_pk_bf16_f32 v70, v74, v70
	v_cvt_pk_bf16_f32 v71, v71, v72
	v_lshlrev_b32_e32 v72, 16, v180
	v_fmac_f32_e32 v72, v66, v130
	v_and_b32_e32 v66, 0xffff0000, v180
	v_fmac_f32_e32 v66, v67, v131
	v_cvt_pk_bf16_f32 v72, v72, v66
	v_lshlrev_b32_e32 v66, 16, v181
	v_fmac_f32_e32 v66, v68, v132
	v_and_b32_e32 v67, 0xffff0000, v181
	v_fmac_f32_e32 v67, v69, v133
	v_cvt_pk_bf16_f32 v73, v66, v67
	v_lshlrev_b32_e32 v66, 16, v174
	v_fmac_f32_e32 v66, v62, v142
	v_and_b32_e32 v62, 0xffff0000, v174
	v_fmac_f32_e32 v62, v63, v143
	v_lshlrev_b32_e32 v63, 16, v175
	v_fmac_f32_e32 v63, v64, v144
	v_and_b32_e32 v64, 0xffff0000, v175
	v_fmac_f32_e32 v64, v65, v145
	global_store_dwordx4 v[200:201], v[70:73], off offset:256
	v_cvt_pk_bf16_f32 v62, v66, v62
	v_cvt_pk_bf16_f32 v63, v63, v64
	v_lshlrev_b32_e32 v64, 16, v176
	v_fmac_f32_e32 v64, v58, v138
	v_and_b32_e32 v58, 0xffff0000, v176
	v_fmac_f32_e32 v58, v59, v139
	v_cvt_pk_bf16_f32 v64, v64, v58
	v_lshlrev_b32_e32 v58, 16, v177
	v_fmac_f32_e32 v58, v60, v140
	v_and_b32_e32 v59, 0xffff0000, v177
	v_fmac_f32_e32 v59, v61, v141
	v_cvt_pk_bf16_f32 v65, v58, v59
	v_lshlrev_b32_e32 v58, 16, v170
	v_fmac_f32_e32 v58, v54, v134
	v_and_b32_e32 v54, 0xffff0000, v170
	v_fmac_f32_e32 v54, v55, v135
	v_lshlrev_b32_e32 v55, 16, v171
	v_fmac_f32_e32 v55, v56, v136
	v_and_b32_e32 v56, 0xffff0000, v171
	v_fmac_f32_e32 v56, v57, v137
	global_store_dwordx4 v[198:199], v[62:65], off
	v_cvt_pk_bf16_f32 v54, v58, v54
	v_cvt_pk_bf16_f32 v55, v55, v56
	v_lshlrev_b32_e32 v56, 16, v172
	v_fmac_f32_e32 v56, v46, v130
	v_and_b32_e32 v46, 0xffff0000, v172
	v_fmac_f32_e32 v46, v47, v131
	v_cvt_pk_bf16_f32 v56, v56, v46
	v_lshlrev_b32_e32 v46, 16, v173
	v_and_b32_e32 v47, 0xffff0000, v173
	v_fmac_f32_e32 v46, v48, v132
	v_fmac_f32_e32 v47, v49, v133
	v_cvt_pk_bf16_f32 v57, v46, v47
	v_lshlrev_b32_e32 v46, 16, v166
	v_and_b32_e32 v47, 0xffff0000, v166
	v_fmac_f32_e32 v46, v50, v142
	v_fmac_f32_e32 v47, v51, v143
	global_store_dwordx4 v[198:199], v[54:57], off offset:256
	v_cvt_pk_bf16_f32 v46, v46, v47
	v_lshlrev_b32_e32 v47, 16, v167
	v_and_b32_e32 v48, 0xffff0000, v167
	v_fmac_f32_e32 v47, v52, v144
	v_fmac_f32_e32 v48, v53, v145
	v_cvt_pk_bf16_f32 v47, v47, v48
	v_lshlrev_b32_e32 v48, 16, v168
	v_fmac_f32_e32 v48, v42, v138
	v_and_b32_e32 v42, 0xffff0000, v168
	v_fmac_f32_e32 v42, v43, v139
	v_cvt_pk_bf16_f32 v48, v48, v42
	v_lshlrev_b32_e32 v42, 16, v169
	v_fmac_f32_e32 v42, v44, v140
	v_and_b32_e32 v43, 0xffff0000, v169
	v_fmac_f32_e32 v43, v45, v141
	v_cvt_pk_bf16_f32 v49, v42, v43
	v_lshlrev_b32_e32 v42, 16, v162
	v_fmac_f32_e32 v42, v38, v134
	v_and_b32_e32 v38, 0xffff0000, v162
	v_fmac_f32_e32 v38, v39, v135
	v_lshlrev_b32_e32 v39, 16, v163
	v_fmac_f32_e32 v39, v40, v136
	v_and_b32_e32 v40, 0xffff0000, v163
	v_fmac_f32_e32 v40, v41, v137
	global_store_dwordx4 v[196:197], v[46:49], off
	v_cvt_pk_bf16_f32 v38, v42, v38
	v_cvt_pk_bf16_f32 v39, v39, v40
	v_lshlrev_b32_e32 v40, 16, v164
	v_fmac_f32_e32 v40, v30, v130
	v_and_b32_e32 v30, 0xffff0000, v164
	v_fmac_f32_e32 v30, v31, v131
	v_cvt_pk_bf16_f32 v40, v40, v30
	v_lshlrev_b32_e32 v30, 16, v165
	v_and_b32_e32 v31, 0xffff0000, v165
	v_fmac_f32_e32 v30, v32, v132
	v_fmac_f32_e32 v31, v33, v133
	v_cvt_pk_bf16_f32 v41, v30, v31
	v_lshlrev_b32_e32 v30, 16, v158
	v_and_b32_e32 v31, 0xffff0000, v158
	v_fmac_f32_e32 v30, v34, v142
	v_fmac_f32_e32 v31, v35, v143
	global_store_dwordx4 v[196:197], v[38:41], off offset:256
	v_cvt_pk_bf16_f32 v30, v30, v31
	v_lshlrev_b32_e32 v31, 16, v159
	v_and_b32_e32 v32, 0xffff0000, v159
	v_fmac_f32_e32 v31, v36, v144
	v_fmac_f32_e32 v32, v37, v145
	v_cvt_pk_bf16_f32 v31, v31, v32
	v_lshlrev_b32_e32 v32, 16, v160
	v_fmac_f32_e32 v32, v26, v138
	v_and_b32_e32 v26, 0xffff0000, v160
	v_fmac_f32_e32 v26, v27, v139
	v_cvt_pk_bf16_f32 v32, v32, v26
	v_lshlrev_b32_e32 v26, 16, v161
	v_fmac_f32_e32 v26, v28, v140
	v_and_b32_e32 v27, 0xffff0000, v161
	v_fmac_f32_e32 v27, v29, v141
	v_cvt_pk_bf16_f32 v33, v26, v27
	v_lshlrev_b32_e32 v26, 16, v154
	v_fmac_f32_e32 v26, v22, v134
	v_and_b32_e32 v22, 0xffff0000, v154
	v_fmac_f32_e32 v22, v23, v135
	v_lshlrev_b32_e32 v23, 16, v155
	v_fmac_f32_e32 v23, v24, v136
	v_and_b32_e32 v24, 0xffff0000, v155
	v_fmac_f32_e32 v24, v25, v137
	global_store_dwordx4 v[194:195], v[30:33], off
	v_cvt_pk_bf16_f32 v22, v26, v22
	v_cvt_pk_bf16_f32 v23, v23, v24
	v_lshlrev_b32_e32 v24, 16, v156
	v_fmac_f32_e32 v24, v12, v130
	v_and_b32_e32 v12, 0xffff0000, v156
	v_fmac_f32_e32 v12, v13, v131
	v_cvt_pk_bf16_f32 v24, v24, v12
	v_lshlrev_b32_e32 v12, 16, v157
	v_and_b32_e32 v13, 0xffff0000, v157
	v_fmac_f32_e32 v12, v14, v132
	v_fmac_f32_e32 v13, v15, v133
	v_cvt_pk_bf16_f32 v25, v12, v13
	v_lshlrev_b32_e32 v12, 16, v150
	v_and_b32_e32 v13, 0xffff0000, v150
	v_fmac_f32_e32 v12, v18, v142
	v_fmac_f32_e32 v13, v19, v143
	global_store_dwordx4 v[194:195], v[22:25], off offset:256
	v_cvt_pk_bf16_f32 v12, v12, v13
	v_lshlrev_b32_e32 v13, 16, v151
	v_and_b32_e32 v14, 0xffff0000, v151
	v_fmac_f32_e32 v13, v20, v144
	v_fmac_f32_e32 v14, v21, v145
	v_cvt_pk_bf16_f32 v13, v13, v14
	v_lshlrev_b32_e32 v14, 16, v152
	v_fmac_f32_e32 v14, v8, v138
	v_and_b32_e32 v8, 0xffff0000, v152
	v_fmac_f32_e32 v8, v9, v139
	v_cvt_pk_bf16_f32 v14, v14, v8
	v_lshlrev_b32_e32 v8, 16, v153
	v_fmac_f32_e32 v8, v10, v140
	v_and_b32_e32 v9, 0xffff0000, v153
	v_fmac_f32_e32 v9, v11, v141
	v_cvt_pk_bf16_f32 v15, v8, v9
	v_lshlrev_b32_e32 v8, 16, v146
	v_fmac_f32_e32 v8, v4, v134
	v_and_b32_e32 v4, 0xffff0000, v146
	v_fmac_f32_e32 v4, v5, v135
	v_lshlrev_b32_e32 v5, 16, v147
	v_fmac_f32_e32 v5, v6, v136
	v_and_b32_e32 v6, 0xffff0000, v147
	v_fmac_f32_e32 v6, v7, v137
	global_store_dwordx4 v[192:193], v[12:15], off
	v_cvt_pk_bf16_f32 v4, v8, v4
	v_cvt_pk_bf16_f32 v5, v5, v6
	v_lshlrev_b32_e32 v6, 16, v148
	v_fmac_f32_e32 v6, v0, v130
	v_and_b32_e32 v0, 0xffff0000, v148
	v_fmac_f32_e32 v0, v1, v131
	v_cvt_pk_bf16_f32 v6, v6, v0
	v_lshlrev_b32_e32 v0, 16, v149
	v_and_b32_e32 v1, 0xffff0000, v149
	s_and_b64 vcc, exec, s[38:39]
	s_mov_b64 s[26:27], -1
	v_fmac_f32_e32 v0, v2, v132
	v_fmac_f32_e32 v1, v3, v133
	v_cvt_pk_bf16_f32 v7, v0, v1
	global_store_dwordx4 v[192:193], v[4:7], off offset:256
	s_cbranch_vccnz .LBB0_984
	s_andn2_b64 vcc, exec, s[0:1]
	s_cbranch_vccnz .LBB0_983
	s_branch .LBB0_983
